# baseline (speedup 1.0000x reference)
; DEV bf16_t f2bf(float f) { unsigned u = __float_as_uint(f); u += 0x7fffu + ((u >> 16) & 1u); return (bf16_t)(u >> 16); }
; DEV int lv(int x) { asm volatile("" : "+v"(x)); return x; }
; DEV int crow(int r, int hi) { return (r & 3) + 8 * (r >> 2) + 4 * hi; }
; template <bool SPREAD>
; DEV void attn_store(f32x16 (&o)[4], const float* __restrict__ gain, float oscale, bf16_t* __restrict__ mix, int q0, int colbase) {
;   const int tid = lv(threadIdx.x), wid = tid >> 6, lane = tid & 63, r32 = lane & 31, hi = lane >> 5;
;   unsigned char* sc = shm_raw + wid * 8704;
;   float gn[4];
; #pragma unroll
;   for (int d = 0; d < 4; ++d) gn[d] = gain[d * 32 + r32] * oscale;
; #pragma unroll
;   for (int r = 0; r < 16; ++r) {
;     float ss = o[0][r] * o[0][r] + o[1][r] * o[1][r] + o[2][r] * o[2][r] + o[3][r] * o[3][r];
;     ss += __shfl_xor(ss, 1); ss += __shfl_xor(ss, 2); ss += __shfl_xor(ss, 4); ss += __shfl_xor(ss, 8); ss += __shfl_xor(ss, 16);
;     const float rn = rsqrtf(ss * (1.f / 128.f) + EPS);
;     const int cr = crow(r, hi);
; #pragma unroll
;     for (int d = 0; d < 4; ++d) *reinterpret_cast<bf16_t*>(sc + cr * 272 + (d * 32 + r32) * 2) = f2bf(o[d][r] * rn * gn[d]);
;   }
.LBB0_366:
	v_mov_b32_e32 v66, v210
	s_xor_b64 s[8:9], s[0:1], -1
	s_barrier
	s_movk_i32 s0, 0x2200
	v_ashrrev_i32_e32 v67, 6, v66
	v_and_b32_e32 v64, 31, v66
	v_mul_lo_u32 v65, v67, s0
	v_readlane_b32 s0, v255, 59
	v_lshlrev_b32_e32 v68, 2, v64
	v_readlane_b32 s1, v255, 60
	s_nop 4
	global_load_dword v72, v68, s[0:1]
	global_load_dword v71, v68, s[0:1] offset:128
	global_load_dword v70, v68, s[0:1] offset:256
	global_load_dword v69, v68, s[0:1] offset:384
	v_add_u32_e32 v68, 0, v65
	v_lshrrev_b32_e32 v65, 3, v66
	v_and_b32_e32 v73, 4, v65
	v_lshlrev_b32_e32 v76, 1, v64
	v_mul_u32_u24_e32 v73, 0x110, v73
	v_mov_b32_e32 v64, v32
	v_mov_b32_e32 v65, v48
	v_add3_u32 v73, v68, v76, v73
	v_mov_b32_e32 v76, v33
	v_mov_b32_e32 v77, v49
	v_pk_mul_f32 v[64:65], v[64:65], v[64:65]
	v_mov_b32_e32 v74, v16
	v_mov_b32_e32 v75, v0
	v_pk_mul_f32 v[76:77], v[76:77], v[76:77]
	v_mov_b32_e32 v78, v17
	v_mov_b32_e32 v79, v1
	v_pk_mul_f32 v[74:75], v[74:75], v[74:75]
	v_pk_mul_f32 v[78:79], v[78:79], v[78:79]
	v_mov_b32_e32 v80, v76
	v_mov_b32_e32 v81, v64
	v_mov_b32_e32 v64, v77
	v_pk_add_f32 v[64:65], v[80:81], v[64:65]
	v_mov_b32_e32 v76, v79
	v_mov_b32_e32 v77, v75
	v_pk_add_f32 v[64:65], v[76:77], v[64:65]
	v_mov_b32_e32 v79, v74
	v_pk_add_f32 v[64:65], v[78:79], v[64:65]
	ds_bpermute_b32 v75, v221, v65
	ds_bpermute_b32 v74, v221, v64
	s_mov_b32 s0, 0x358637bd
	s_brev_b32 s4, 60
	s_add_i32 s16, 0, 0x18000
	s_add_i32 s15, 0, 0x10000
	s_waitcnt lgkmcnt(0)
	v_pk_add_f32 v[64:65], v[64:65], v[74:75]
	ds_bpermute_b32 v75, v220, v65
	ds_bpermute_b32 v74, v220, v64
	s_add_i32 s14, s75, 4
	s_waitcnt lgkmcnt(0)
	v_pk_add_f32 v[64:65], v[64:65], v[74:75]
	ds_bpermute_b32 v75, v219, v65
	ds_bpermute_b32 v74, v219, v64
	s_waitcnt lgkmcnt(0)
	v_pk_add_f32 v[64:65], v[64:65], v[74:75]
	ds_bpermute_b32 v75, v218, v65
	ds_bpermute_b32 v74, v218, v64
	s_waitcnt lgkmcnt(0)
	v_pk_add_f32 v[64:65], v[64:65], v[74:75]
	ds_bpermute_b32 v75, v217, v65
	ds_bpermute_b32 v74, v217, v64
	s_waitcnt lgkmcnt(0)
	v_pk_add_f32 v[74:75], v[64:65], v[74:75]
	v_mov_b64_e32 v[64:65], s[0:1]
	v_pk_fma_f32 v[74:75], v[74:75], s[4:5], v[64:65] op_sel_hi:[1,0,0]
	s_nop 0
	v_mul_f32_e32 v76, 0x4b800000, v75
	v_cmp_gt_f32_e64 s[0:1], s33, v75
	v_cmp_gt_f32_e32 vcc, s33, v74
	s_nop 0
	v_cndmask_b32_e64 v75, v75, v76, s[0:1]
	v_rsq_f32_e32 v75, v75
	s_nop 0
	v_mul_f32_e32 v76, 0x45800000, v75
	v_cndmask_b32_e64 v75, v75, v76, s[0:1]
	v_mul_f32_e32 v48, v48, v75
	s_waitcnt vmcnt(3)
	v_mul_f32_e32 v48, v72, v48
	v_bfe_u32 v76, v48, 16, 1
	v_mul_f32_e32 v32, v32, v75
	v_add3_u32 v48, v48, v76, s2
	s_waitcnt vmcnt(2)
	v_mul_f32_e32 v32, v71, v32
	ds_write_b16_d16_hi v73, v48
	v_bfe_u32 v48, v32, 16, 1
	v_mul_f32_e32 v0, v0, v75
	v_add3_u32 v32, v32, v48, s2
	s_waitcnt vmcnt(1)
	v_mul_f32_e32 v0, v70, v0
	ds_write_b16_d16_hi v73, v32 offset:64
	v_bfe_u32 v32, v0, 16, 1
	v_add3_u32 v0, v0, v32, s2
	ds_write_b16_d16_hi v73, v0 offset:128
	v_mul_f32_e32 v0, v16, v75
	s_waitcnt vmcnt(0)
	v_mul_f32_e32 v0, v69, v0
	v_bfe_u32 v16, v0, 16, 1
	v_add3_u32 v0, v0, v16, s2
	ds_write_b16_d16_hi v73, v0 offset:192
	v_mul_f32_e32 v0, 0x4b800000, v74
	v_cndmask_b32_e32 v0, v74, v0, vcc
	v_rsq_f32_e32 v0, v0
	v_mov_b32_e32 v48, v19
	v_mul_f32_e32 v16, 0x45800000, v0
	v_cndmask_b32_e32 v0, v0, v16, vcc
	v_mul_f32_e32 v16, v49, v0
	v_mul_f32_e32 v16, v72, v16
	v_bfe_u32 v32, v16, 16, 1
	v_add3_u32 v16, v16, v32, s2
	ds_write_b16_d16_hi v73, v16 offset:272
	v_mul_f32_e32 v16, v33, v0
	v_mul_f32_e32 v16, v71, v16
	v_bfe_u32 v32, v16, 16, 1
	v_mul_f32_e32 v1, v1, v0
	v_add3_u32 v16, v16, v32, s2
	v_mul_f32_e32 v1, v70, v1
	ds_write_b16_d16_hi v73, v16 offset:336
	v_bfe_u32 v16, v1, 16, 1
	v_mul_f32_e32 v0, v17, v0
	v_add3_u32 v1, v1, v16, s2
	v_mul_f32_e32 v0, v69, v0
	ds_write_b16_d16_hi v73, v1 offset:400
	v_bfe_u32 v1, v0, 16, 1
	v_add3_u32 v0, v0, v1, s2
	ds_write_b16_d16_hi v73, v0 offset:464
	v_mov_b32_e32 v0, v34
	v_mov_b32_e32 v1, v50
	v_mov_b32_e32 v32, v35
	v_mov_b32_e32 v33, v51
	v_pk_mul_f32 v[0:1], v[0:1], v[0:1]
	v_mov_b32_e32 v16, v18
	v_mov_b32_e32 v17, v2
	v_pk_mul_f32 v[32:33], v[32:33], v[32:33]
	v_mov_b32_e32 v49, v3
	v_pk_mul_f32 v[16:17], v[16:17], v[16:17]
	v_pk_mul_f32 v[48:49], v[48:49], v[48:49]
	v_mov_b32_e32 v74, v32
	v_mov_b32_e32 v75, v0
	v_mov_b32_e32 v0, v33
	v_pk_add_f32 v[0:1], v[74:75], v[0:1]
	v_mov_b32_e32 v32, v49
	v_mov_b32_e32 v33, v17
	v_pk_add_f32 v[0:1], v[32:33], v[0:1]
	v_mov_b32_e32 v49, v16
	v_pk_add_f32 v[0:1], v[48:49], v[0:1]
	ds_bpermute_b32 v17, v221, v1
	ds_bpermute_b32 v16, v221, v0
	s_waitcnt lgkmcnt(0)
	v_pk_add_f32 v[0:1], v[0:1], v[16:17]
	ds_bpermute_b32 v17, v220, v1
	ds_bpermute_b32 v16, v220, v0
	s_waitcnt lgkmcnt(0)
	v_pk_add_f32 v[0:1], v[0:1], v[16:17]
	ds_bpermute_b32 v17, v219, v1
	ds_bpermute_b32 v16, v219, v0
	s_waitcnt lgkmcnt(0)
	v_pk_add_f32 v[0:1], v[0:1], v[16:17]
	ds_bpermute_b32 v17, v218, v1
	ds_bpermute_b32 v16, v218, v0
	s_waitcnt lgkmcnt(0)
	v_pk_add_f32 v[0:1], v[0:1], v[16:17]
	ds_bpermute_b32 v17, v217, v1
	ds_bpermute_b32 v16, v217, v0
	s_waitcnt lgkmcnt(0)
; DEV bf16_t f2bf(float f) { unsigned u = __float_as_uint(f); u += 0x7fffu + ((u >> 16) & 1u); return (bf16_t)(u >> 16); }
; DEV int crow(int r, int hi) { return (r & 3) + 8 * (r >> 2) + 4 * hi; }
; template <bool SPREAD>
; DEV void attn_store(f32x16 (&o)[4], const float* __restrict__ gain, float oscale, bf16_t* __restrict__ mix, int q0, int colbase) {
;     ...
;   for (int r = 0; r < 16; ++r) {
;     float ss = o[0][r] * o[0][r] + o[1][r] * o[1][r] + o[2][r] * o[2][r] + o[3][r] * o[3][r];
;     ss += __shfl_xor(ss, 1); ss += __shfl_xor(ss, 2); ss += __shfl_xor(ss, 4); ss += __shfl_xor(ss, 8); ss += __shfl_xor(ss, 16);
;     const float rn = rsqrtf(ss * (1.f / 128.f) + EPS);
;     const int cr = crow(r, hi);
; #pragma unroll
;     for (int d = 0; d < 4; ++d) *reinterpret_cast<bf16_t*>(sc + cr * 272 + (d * 32 + r32) * 2) = f2bf(o[d][r] * rn * gn[d]);
;   }
	v_pk_add_f32 v[0:1], v[0:1], v[16:17]
	s_nop 0
	v_pk_fma_f32 v[0:1], v[0:1], s[4:5], v[64:65] op_sel_hi:[1,0,0]
	s_nop 0
	v_mul_f32_e32 v16, 0x4b800000, v1
	v_cmp_gt_f32_e64 s[0:1], s33, v1
	v_cmp_gt_f32_e32 vcc, s33, v0
	s_nop 0
	v_cndmask_b32_e64 v1, v1, v16, s[0:1]
	v_rsq_f32_e32 v1, v1
	s_nop 0
	v_mul_f32_e32 v16, 0x45800000, v1
	v_cndmask_b32_e64 v1, v1, v16, s[0:1]
	v_mul_f32_e32 v16, v50, v1
	v_mul_f32_e32 v16, v72, v16
	v_bfe_u32 v17, v16, 16, 1
	v_add3_u32 v16, v16, v17, s2
	ds_write_b16_d16_hi v73, v16 offset:544
	v_mul_f32_e32 v16, v34, v1
	v_mul_f32_e32 v16, v71, v16
	v_bfe_u32 v17, v16, 16, 1
	v_mul_f32_e32 v2, v2, v1
	v_add3_u32 v16, v16, v17, s2
	v_mul_f32_e32 v2, v70, v2
	ds_write_b16_d16_hi v73, v16 offset:608
	v_bfe_u32 v16, v2, 16, 1
	v_mul_f32_e32 v1, v18, v1
	v_add3_u32 v2, v2, v16, s2
	v_mul_f32_e32 v1, v69, v1
	ds_write_b16_d16_hi v73, v2 offset:672
	v_bfe_u32 v2, v1, 16, 1
	v_add3_u32 v1, v1, v2, s2
	ds_write_b16_d16_hi v73, v1 offset:736
	v_mul_f32_e32 v1, 0x4b800000, v0
	v_cndmask_b32_e32 v0, v0, v1, vcc
	v_rsq_f32_e32 v0, v0
	v_mov_b32_e32 v16, v37
	v_mov_b32_e32 v17, v53
	v_pk_mul_f32 v[16:17], v[16:17], v[16:17]
	v_mul_f32_e32 v1, 0x45800000, v0
	v_cndmask_b32_e32 v0, v0, v1, vcc
	v_mul_f32_e32 v1, v51, v0
	v_mul_f32_e32 v1, v72, v1
	v_bfe_u32 v2, v1, 16, 1
	v_add3_u32 v1, v1, v2, s2
	ds_write_b16_d16_hi v73, v1 offset:816
	v_mul_f32_e32 v1, v35, v0
	v_mul_f32_e32 v1, v71, v1
	v_bfe_u32 v2, v1, 16, 1
	v_add3_u32 v1, v1, v2, s2
	ds_write_b16_d16_hi v73, v1 offset:880
	v_mul_f32_e32 v1, v3, v0
	v_mul_f32_e32 v1, v70, v1
	v_bfe_u32 v2, v1, 16, 1
	v_mul_f32_e32 v0, v19, v0
	v_add3_u32 v1, v1, v2, s2
	v_mul_f32_e32 v0, v69, v0
	ds_write_b16_d16_hi v73, v1 offset:944
	v_bfe_u32 v1, v0, 16, 1
	v_add3_u32 v0, v0, v1, s2
	ds_write_b16_d16_hi v73, v0 offset:1008
	v_mov_b32_e32 v0, v36
	v_mov_b32_e32 v1, v52
	v_pk_mul_f32 v[0:1], v[0:1], v[0:1]
	v_mov_b32_e32 v2, v20
	v_mov_b32_e32 v3, v4
	v_mov_b32_e32 v18, v21
	v_mov_b32_e32 v19, v5
	v_pk_mul_f32 v[2:3], v[2:3], v[2:3]
	v_pk_mul_f32 v[18:19], v[18:19], v[18:19]
	v_mov_b32_e32 v32, v16
	v_mov_b32_e32 v33, v0
	v_mov_b32_e32 v0, v17
	v_pk_add_f32 v[0:1], v[32:33], v[0:1]
	v_mov_b32_e32 v16, v19
	v_mov_b32_e32 v17, v3
	v_pk_add_f32 v[0:1], v[16:17], v[0:1]
	v_mov_b32_e32 v19, v2
	v_pk_add_f32 v[0:1], v[18:19], v[0:1]
	ds_bpermute_b32 v3, v221, v1
	ds_bpermute_b32 v2, v221, v0
	v_mov_b32_e32 v16, v23
	v_mov_b32_e32 v17, v7
	v_pk_mul_f32 v[16:17], v[16:17], v[16:17]
	s_waitcnt lgkmcnt(0)
	v_pk_add_f32 v[0:1], v[0:1], v[2:3]
	ds_bpermute_b32 v3, v220, v1
	ds_bpermute_b32 v2, v220, v0
	s_waitcnt lgkmcnt(0)
	v_pk_add_f32 v[0:1], v[0:1], v[2:3]
	ds_bpermute_b32 v3, v219, v1
	ds_bpermute_b32 v2, v219, v0
	s_waitcnt lgkmcnt(0)
	v_pk_add_f32 v[0:1], v[0:1], v[2:3]
	ds_bpermute_b32 v3, v218, v1
	ds_bpermute_b32 v2, v218, v0
	s_waitcnt lgkmcnt(0)
	v_pk_add_f32 v[0:1], v[0:1], v[2:3]
	ds_bpermute_b32 v3, v217, v1
	ds_bpermute_b32 v2, v217, v0
	s_waitcnt lgkmcnt(0)
	v_pk_add_f32 v[0:1], v[0:1], v[2:3]
	s_nop 0
	v_pk_fma_f32 v[0:1], v[0:1], s[4:5], v[64:65] op_sel_hi:[1,0,0]
	s_nop 0
	v_mul_f32_e32 v2, 0x4b800000, v1
	v_cmp_gt_f32_e64 s[0:1], s33, v1
	v_cmp_gt_f32_e32 vcc, s33, v0
	s_nop 0
	v_cndmask_b32_e64 v1, v1, v2, s[0:1]
	v_rsq_f32_e32 v1, v1
	s_nop 0
	v_mul_f32_e32 v2, 0x45800000, v1
	v_cndmask_b32_e64 v1, v1, v2, s[0:1]
	v_mul_f32_e32 v2, v52, v1
	v_mul_f32_e32 v2, v72, v2
	v_bfe_u32 v3, v2, 16, 1
	v_add3_u32 v2, v2, v3, s2
	ds_write_b16_d16_hi v73, v2 offset:2176
	v_mul_f32_e32 v2, v36, v1
	v_mul_f32_e32 v2, v71, v2
	v_bfe_u32 v3, v2, 16, 1
	v_add3_u32 v2, v2, v3, s2
	ds_write_b16_d16_hi v73, v2 offset:2240
	v_mul_f32_e32 v2, v4, v1
	v_mul_f32_e32 v2, v70, v2
	v_bfe_u32 v3, v2, 16, 1
	v_mul_f32_e32 v1, v20, v1
	v_add3_u32 v2, v2, v3, s2
	v_mul_f32_e32 v1, v69, v1
	ds_write_b16_d16_hi v73, v2 offset:2304
	v_bfe_u32 v2, v1, 16, 1
	v_add3_u32 v1, v1, v2, s2
	ds_write_b16_d16_hi v73, v1 offset:2368
	v_mul_f32_e32 v1, 0x4b800000, v0
	v_cndmask_b32_e32 v0, v0, v1, vcc
	v_rsq_f32_e32 v0, v0
	v_mov_b32_e32 v4, v39
	v_mov_b32_e32 v3, v6
	v_mul_f32_e32 v1, 0x45800000, v0
	v_cndmask_b32_e32 v0, v0, v1, vcc
	v_mul_f32_e32 v1, v53, v0
	v_mul_f32_e32 v1, v72, v1
	v_bfe_u32 v2, v1, 16, 1
	v_add3_u32 v1, v1, v2, s2
	ds_write_b16_d16_hi v73, v1 offset:2448
	v_mul_f32_e32 v1, v37, v0
	v_mul_f32_e32 v1, v71, v1
	v_bfe_u32 v2, v1, 16, 1
	v_add3_u32 v1, v1, v2, s2
	ds_write_b16_d16_hi v73, v1 offset:2512
	v_mul_f32_e32 v1, v5, v0
	v_mul_f32_e32 v1, v70, v1
	v_bfe_u32 v2, v1, 16, 1
	v_mul_f32_e32 v0, v21, v0
	v_add3_u32 v1, v1, v2, s2
	v_mul_f32_e32 v0, v69, v0
	ds_write_b16_d16_hi v73, v1 offset:2576
	v_bfe_u32 v1, v0, 16, 1
	v_add3_u32 v0, v0, v1, s2
	ds_write_b16_d16_hi v73, v0 offset:2640
	v_mov_b32_e32 v0, v38
	v_mov_b32_e32 v1, v54
	v_mov_b32_e32 v5, v55
	v_pk_mul_f32 v[0:1], v[0:1], v[0:1]
	v_mov_b32_e32 v2, v22
	v_pk_mul_f32 v[4:5], v[4:5], v[4:5]
	v_pk_mul_f32 v[2:3], v[2:3], v[2:3]
	v_mov_b32_e32 v18, v4
	v_mov_b32_e32 v19, v0
	v_mov_b32_e32 v0, v5
	v_pk_add_f32 v[0:1], v[18:19], v[0:1]
	v_mov_b32_e32 v4, v17
	v_mov_b32_e32 v5, v3
	v_pk_add_f32 v[0:1], v[4:5], v[0:1]
	v_mov_b32_e32 v17, v2
	v_pk_add_f32 v[0:1], v[16:17], v[0:1]
	ds_bpermute_b32 v3, v221, v1
	ds_bpermute_b32 v2, v221, v0
	v_mov_b32_e32 v4, v41
	v_mov_b32_e32 v5, v57
	v_pk_mul_f32 v[4:5], v[4:5], v[4:5]
	s_waitcnt lgkmcnt(0)
	v_pk_add_f32 v[0:1], v[0:1], v[2:3]
	ds_bpermute_b32 v3, v220, v1
	ds_bpermute_b32 v2, v220, v0
	v_mov_b32_e32 v16, v4
	s_waitcnt lgkmcnt(0)
	v_pk_add_f32 v[0:1], v[0:1], v[2:3]
	ds_bpermute_b32 v3, v219, v1
	ds_bpermute_b32 v2, v219, v0
	s_waitcnt lgkmcnt(0)
; DEV bf16_t f2bf(float f) { unsigned u = __float_as_uint(f); u += 0x7fffu + ((u >> 16) & 1u); return (bf16_t)(u >> 16); }
; DEV int crow(int r, int hi) { return (r & 3) + 8 * (r >> 2) + 4 * hi; }
; template <bool SPREAD>
; DEV void attn_store(f32x16 (&o)[4], const float* __restrict__ gain, float oscale, bf16_t* __restrict__ mix, int q0, int colbase) {
;     ...
;   for (int r = 0; r < 16; ++r) {
;     float ss = o[0][r] * o[0][r] + o[1][r] * o[1][r] + o[2][r] * o[2][r] + o[3][r] * o[3][r];
;     ss += __shfl_xor(ss, 1); ss += __shfl_xor(ss, 2); ss += __shfl_xor(ss, 4); ss += __shfl_xor(ss, 8); ss += __shfl_xor(ss, 16);
;     const float rn = rsqrtf(ss * (1.f / 128.f) + EPS);
;     const int cr = crow(r, hi);
; #pragma unroll
;     for (int d = 0; d < 4; ++d) *reinterpret_cast<bf16_t*>(sc + cr * 272 + (d * 32 + r32) * 2) = f2bf(o[d][r] * rn * gn[d]);
;   }
	v_pk_add_f32 v[0:1], v[0:1], v[2:3]
	ds_bpermute_b32 v3, v218, v1
	ds_bpermute_b32 v2, v218, v0
	s_waitcnt lgkmcnt(0)
	v_pk_add_f32 v[0:1], v[0:1], v[2:3]
	ds_bpermute_b32 v3, v217, v1
	ds_bpermute_b32 v2, v217, v0
	s_waitcnt lgkmcnt(0)
	v_pk_add_f32 v[0:1], v[0:1], v[2:3]
	s_nop 0
	v_pk_fma_f32 v[0:1], v[0:1], s[4:5], v[64:65] op_sel_hi:[1,0,0]
	s_nop 0
	v_mul_f32_e32 v2, 0x4b800000, v1
	v_cmp_gt_f32_e64 s[0:1], s33, v1
	v_cmp_gt_f32_e32 vcc, s33, v0
	s_nop 0
	v_cndmask_b32_e64 v1, v1, v2, s[0:1]
	v_rsq_f32_e32 v1, v1
	s_nop 0
	v_mul_f32_e32 v2, 0x45800000, v1
	v_cndmask_b32_e64 v1, v1, v2, s[0:1]
	v_mul_f32_e32 v2, v54, v1
	v_mul_f32_e32 v2, v72, v2
	v_bfe_u32 v3, v2, 16, 1
	v_add3_u32 v2, v2, v3, s2
	ds_write_b16_d16_hi v73, v2 offset:2720
	v_mul_f32_e32 v2, v38, v1
	v_mul_f32_e32 v2, v71, v2
	v_bfe_u32 v3, v2, 16, 1
	v_add3_u32 v2, v2, v3, s2
	ds_write_b16_d16_hi v73, v2 offset:2784
	v_mul_f32_e32 v2, v6, v1
	v_mul_f32_e32 v2, v70, v2
	v_bfe_u32 v3, v2, 16, 1
	v_mul_f32_e32 v1, v22, v1
	v_add3_u32 v2, v2, v3, s2
	v_mul_f32_e32 v1, v69, v1
	ds_write_b16_d16_hi v73, v2 offset:2848
	v_bfe_u32 v2, v1, 16, 1
	v_add3_u32 v1, v1, v2, s2
	ds_write_b16_d16_hi v73, v1 offset:2912
	v_mul_f32_e32 v1, 0x4b800000, v0
	v_cndmask_b32_e32 v0, v0, v1, vcc
	v_rsq_f32_e32 v0, v0
	v_mov_b32_e32 v3, v8
	v_mov_b32_e32 v6, v25
	v_mul_f32_e32 v1, 0x45800000, v0
	v_cndmask_b32_e32 v0, v0, v1, vcc
	v_mul_f32_e32 v1, v55, v0
	v_mul_f32_e32 v1, v72, v1
	v_bfe_u32 v2, v1, 16, 1
	v_add3_u32 v1, v1, v2, s2
	ds_write_b16_d16_hi v73, v1 offset:2992
	v_mul_f32_e32 v1, v39, v0
	v_mul_f32_e32 v1, v71, v1
	v_bfe_u32 v2, v1, 16, 1
	v_add3_u32 v1, v1, v2, s2
	ds_write_b16_d16_hi v73, v1 offset:3056
	v_mul_f32_e32 v1, v7, v0
	v_mul_f32_e32 v1, v70, v1
	v_bfe_u32 v2, v1, 16, 1
	v_mul_f32_e32 v0, v23, v0
	v_add3_u32 v1, v1, v2, s2
	v_mul_f32_e32 v0, v69, v0
	ds_write_b16_d16_hi v73, v1 offset:3120
	v_bfe_u32 v1, v0, 16, 1
	v_add3_u32 v0, v0, v1, s2
	ds_write_b16_d16_hi v73, v0 offset:3184
	v_mov_b32_e32 v0, v40
	v_mov_b32_e32 v1, v56
	v_pk_mul_f32 v[0:1], v[0:1], v[0:1]
	v_mov_b32_e32 v2, v24
	v_mov_b32_e32 v7, v9
	v_pk_mul_f32 v[2:3], v[2:3], v[2:3]
	v_pk_mul_f32 v[6:7], v[6:7], v[6:7]
	v_mov_b32_e32 v17, v0
	v_mov_b32_e32 v0, v5
	v_pk_add_f32 v[0:1], v[16:17], v[0:1]
	v_mov_b32_e32 v4, v7
	v_mov_b32_e32 v5, v3
	v_pk_add_f32 v[0:1], v[4:5], v[0:1]
	v_mov_b32_e32 v7, v2
	v_pk_add_f32 v[0:1], v[6:7], v[0:1]
	ds_bpermute_b32 v3, v221, v1
	ds_bpermute_b32 v2, v221, v0
	v_mov_b32_e32 v4, v43
	v_mov_b32_e32 v5, v59
	v_pk_mul_f32 v[4:5], v[4:5], v[4:5]
	v_mov_b32_e32 v6, v27
	s_waitcnt lgkmcnt(0)
	v_pk_add_f32 v[0:1], v[0:1], v[2:3]
	ds_bpermute_b32 v3, v220, v1
	ds_bpermute_b32 v2, v220, v0
	v_mov_b32_e32 v7, v11
	v_pk_mul_f32 v[6:7], v[6:7], v[6:7]
	v_mov_b32_e32 v17, 0x2000
	s_waitcnt lgkmcnt(0)
	v_pk_add_f32 v[0:1], v[0:1], v[2:3]
	ds_bpermute_b32 v3, v219, v1
	ds_bpermute_b32 v2, v219, v0
	s_waitcnt lgkmcnt(0)
	v_pk_add_f32 v[0:1], v[0:1], v[2:3]
	ds_bpermute_b32 v3, v218, v1
	ds_bpermute_b32 v2, v218, v0
	s_waitcnt lgkmcnt(0)
	v_pk_add_f32 v[0:1], v[0:1], v[2:3]
	ds_bpermute_b32 v3, v217, v1
	ds_bpermute_b32 v2, v217, v0
	s_waitcnt lgkmcnt(0)
	v_pk_add_f32 v[0:1], v[0:1], v[2:3]
	s_nop 0
	v_pk_fma_f32 v[0:1], v[0:1], s[4:5], v[64:65] op_sel_hi:[1,0,0]
	s_nop 0
	v_mul_f32_e32 v2, 0x4b800000, v1
	v_cmp_gt_f32_e64 s[0:1], s33, v1
	v_cmp_gt_f32_e32 vcc, s33, v0
	s_nop 0
	v_cndmask_b32_e64 v1, v1, v2, s[0:1]
	v_rsq_f32_e32 v1, v1
	s_nop 0
	v_mul_f32_e32 v2, 0x45800000, v1
	v_cndmask_b32_e64 v1, v1, v2, s[0:1]
	v_mul_f32_e32 v2, v56, v1
	v_mul_f32_e32 v2, v72, v2
	v_bfe_u32 v3, v2, 16, 1
	v_add3_u32 v2, v2, v3, s2
	ds_write_b16_d16_hi v73, v2 offset:4352
	v_mul_f32_e32 v2, v40, v1
	v_mul_f32_e32 v2, v71, v2
	v_bfe_u32 v3, v2, 16, 1
	v_add3_u32 v2, v2, v3, s2
	ds_write_b16_d16_hi v73, v2 offset:4416
	v_mul_f32_e32 v2, v8, v1
	v_mul_f32_e32 v2, v70, v2
	v_bfe_u32 v3, v2, 16, 1
	v_mul_f32_e32 v1, v24, v1
	v_add3_u32 v2, v2, v3, s2
	v_mul_f32_e32 v1, v69, v1
	ds_write_b16_d16_hi v73, v2 offset:4480
	v_bfe_u32 v2, v1, 16, 1
	v_add3_u32 v1, v1, v2, s2
	ds_write_b16_d16_hi v73, v1 offset:4544
	v_mul_f32_e32 v1, 0x4b800000, v0
	v_cndmask_b32_e32 v0, v0, v1, vcc
	v_rsq_f32_e32 v0, v0
	v_mov_b32_e32 v3, v10
	v_mov_b32_e32 v8, v4
	v_mov_b32_e32 v4, v7
	v_mul_f32_e32 v1, 0x45800000, v0
	v_cndmask_b32_e32 v0, v0, v1, vcc
	v_mul_f32_e32 v1, v57, v0
	v_mul_f32_e32 v1, v72, v1
	v_bfe_u32 v2, v1, 16, 1
	v_add3_u32 v1, v1, v2, s2
	ds_write_b16_d16_hi v73, v1 offset:4624
	v_mul_f32_e32 v1, v41, v0
	v_mul_f32_e32 v1, v71, v1
	v_bfe_u32 v2, v1, 16, 1
	v_add3_u32 v1, v1, v2, s2
	ds_write_b16_d16_hi v73, v1 offset:4688
	v_mul_f32_e32 v1, v9, v0
	v_mul_f32_e32 v1, v70, v1
	v_bfe_u32 v2, v1, 16, 1
	v_mul_f32_e32 v0, v25, v0
	v_add3_u32 v1, v1, v2, s2
	v_mul_f32_e32 v0, v69, v0
	ds_write_b16_d16_hi v73, v1 offset:4752
	v_bfe_u32 v1, v0, 16, 1
	v_add3_u32 v0, v0, v1, s2
	ds_write_b16_d16_hi v73, v0 offset:4816
	v_mov_b32_e32 v0, v42
	v_mov_b32_e32 v1, v58
	v_pk_mul_f32 v[0:1], v[0:1], v[0:1]
	v_mov_b32_e32 v2, v26
	v_pk_mul_f32 v[2:3], v[2:3], v[2:3]
	v_mov_b32_e32 v9, v0
	v_mov_b32_e32 v0, v5
	v_pk_add_f32 v[0:1], v[8:9], v[0:1]
	v_mov_b32_e32 v5, v3
	v_pk_add_f32 v[0:1], v[4:5], v[0:1]
	v_mov_b32_e32 v7, v2
	v_pk_add_f32 v[0:1], v[6:7], v[0:1]
	ds_bpermute_b32 v3, v221, v1
	ds_bpermute_b32 v2, v221, v0
	v_mov_b32_e32 v4, v45
	v_mov_b32_e32 v5, v61
	v_pk_mul_f32 v[4:5], v[4:5], v[4:5]
	v_mov_b32_e32 v6, v29
	s_waitcnt lgkmcnt(0)
	v_pk_add_f32 v[0:1], v[0:1], v[2:3]
	ds_bpermute_b32 v3, v220, v1
	ds_bpermute_b32 v2, v220, v0
	v_mov_b32_e32 v7, v13
	v_pk_mul_f32 v[6:7], v[6:7], v[6:7]
	v_mov_b32_e32 v8, v4
	v_mov_b32_e32 v4, v7
	s_waitcnt lgkmcnt(0)
; DEV bf16_t f2bf(float f) { unsigned u = __float_as_uint(f); u += 0x7fffu + ((u >> 16) & 1u); return (bf16_t)(u >> 16); }
; DEV int crow(int r, int hi) { return (r & 3) + 8 * (r >> 2) + 4 * hi; }
; template <bool SPREAD>
; DEV void attn_store(f32x16 (&o)[4], const float* __restrict__ gain, float oscale, bf16_t* __restrict__ mix, int q0, int colbase) {
;     ...
;   for (int r = 0; r < 16; ++r) {
;     float ss = o[0][r] * o[0][r] + o[1][r] * o[1][r] + o[2][r] * o[2][r] + o[3][r] * o[3][r];
;     ss += __shfl_xor(ss, 1); ss += __shfl_xor(ss, 2); ss += __shfl_xor(ss, 4); ss += __shfl_xor(ss, 8); ss += __shfl_xor(ss, 16);
;     const float rn = rsqrtf(ss * (1.f / 128.f) + EPS);
;     const int cr = crow(r, hi);
; #pragma unroll
;     for (int d = 0; d < 4; ++d) *reinterpret_cast<bf16_t*>(sc + cr * 272 + (d * 32 + r32) * 2) = f2bf(o[d][r] * rn * gn[d]);
;   }
	v_pk_add_f32 v[0:1], v[0:1], v[2:3]
	ds_bpermute_b32 v3, v219, v1
	ds_bpermute_b32 v2, v219, v0
	s_waitcnt lgkmcnt(0)
	v_pk_add_f32 v[0:1], v[0:1], v[2:3]
	ds_bpermute_b32 v3, v218, v1
	ds_bpermute_b32 v2, v218, v0
	s_waitcnt lgkmcnt(0)
	v_pk_add_f32 v[0:1], v[0:1], v[2:3]
	ds_bpermute_b32 v3, v217, v1
	ds_bpermute_b32 v2, v217, v0
	s_waitcnt lgkmcnt(0)
	v_pk_add_f32 v[0:1], v[0:1], v[2:3]
	s_nop 0
	v_pk_fma_f32 v[0:1], v[0:1], s[4:5], v[64:65] op_sel_hi:[1,0,0]
	s_nop 0
	v_mul_f32_e32 v2, 0x4b800000, v1
	v_cmp_gt_f32_e64 s[0:1], s33, v1
	v_cmp_gt_f32_e32 vcc, s33, v0
	s_nop 0
	v_cndmask_b32_e64 v1, v1, v2, s[0:1]
	v_rsq_f32_e32 v1, v1
	s_nop 0
	v_mul_f32_e32 v2, 0x45800000, v1
	v_cndmask_b32_e64 v1, v1, v2, s[0:1]
	v_mul_f32_e32 v2, v58, v1
	v_mul_f32_e32 v2, v72, v2
	v_bfe_u32 v3, v2, 16, 1
	v_add3_u32 v2, v2, v3, s2
	ds_write_b16_d16_hi v73, v2 offset:4896
	v_mul_f32_e32 v2, v42, v1
	v_mul_f32_e32 v2, v71, v2
	v_bfe_u32 v3, v2, 16, 1
	v_add3_u32 v2, v2, v3, s2
	ds_write_b16_d16_hi v73, v2 offset:4960
	v_mul_f32_e32 v2, v10, v1
	v_mul_f32_e32 v2, v70, v2
	v_bfe_u32 v3, v2, 16, 1
	v_mul_f32_e32 v1, v26, v1
	v_add3_u32 v2, v2, v3, s2
	v_mul_f32_e32 v1, v69, v1
	ds_write_b16_d16_hi v73, v2 offset:5024
	v_bfe_u32 v2, v1, 16, 1
	v_add3_u32 v1, v1, v2, s2
	ds_write_b16_d16_hi v73, v1 offset:5088
	v_mul_f32_e32 v1, 0x4b800000, v0
	v_cndmask_b32_e32 v0, v0, v1, vcc
	v_rsq_f32_e32 v0, v0
	v_mov_b32_e32 v3, v12
	v_mul_f32_e32 v1, 0x45800000, v0
	v_cndmask_b32_e32 v0, v0, v1, vcc
	v_mul_f32_e32 v1, v59, v0
	v_mul_f32_e32 v1, v72, v1
	v_bfe_u32 v2, v1, 16, 1
	v_add3_u32 v1, v1, v2, s2
	ds_write_b16_d16_hi v73, v1 offset:5168
	v_mul_f32_e32 v1, v43, v0
	v_mul_f32_e32 v1, v71, v1
	v_bfe_u32 v2, v1, 16, 1
	v_add3_u32 v1, v1, v2, s2
	ds_write_b16_d16_hi v73, v1 offset:5232
	v_mul_f32_e32 v1, v11, v0
	v_mul_f32_e32 v1, v70, v1
	v_bfe_u32 v2, v1, 16, 1
	v_mul_f32_e32 v0, v27, v0
	v_add3_u32 v1, v1, v2, s2
	v_mul_f32_e32 v0, v69, v0
	ds_write_b16_d16_hi v73, v1 offset:5296
	v_bfe_u32 v1, v0, 16, 1
	v_add3_u32 v0, v0, v1, s2
	ds_write_b16_d16_hi v73, v0 offset:5360
	v_mov_b32_e32 v0, v44
	v_mov_b32_e32 v1, v60
	v_pk_mul_f32 v[0:1], v[0:1], v[0:1]
	v_mov_b32_e32 v2, v28
	v_pk_mul_f32 v[2:3], v[2:3], v[2:3]
	v_mov_b32_e32 v9, v0
	v_mov_b32_e32 v0, v5
	v_pk_add_f32 v[0:1], v[8:9], v[0:1]
	v_mov_b32_e32 v5, v3
	v_pk_add_f32 v[0:1], v[4:5], v[0:1]
	v_mov_b32_e32 v7, v2
	v_pk_add_f32 v[0:1], v[6:7], v[0:1]
	ds_bpermute_b32 v3, v221, v1
	ds_bpermute_b32 v2, v221, v0
	v_mov_b32_e32 v4, v47
	v_mov_b32_e32 v5, v63
	v_pk_mul_f32 v[4:5], v[4:5], v[4:5]
	v_mov_b32_e32 v6, v31
	s_waitcnt lgkmcnt(0)
	v_pk_add_f32 v[0:1], v[0:1], v[2:3]
	ds_bpermute_b32 v3, v220, v1
	ds_bpermute_b32 v2, v220, v0
	v_mov_b32_e32 v7, v15
	v_pk_mul_f32 v[6:7], v[6:7], v[6:7]
	v_mov_b32_e32 v8, v4
	v_mov_b32_e32 v4, v7
	s_waitcnt lgkmcnt(0)
	v_pk_add_f32 v[0:1], v[0:1], v[2:3]
	ds_bpermute_b32 v3, v219, v1
	ds_bpermute_b32 v2, v219, v0
	s_waitcnt lgkmcnt(0)
	v_pk_add_f32 v[0:1], v[0:1], v[2:3]
	ds_bpermute_b32 v3, v218, v1
	ds_bpermute_b32 v2, v218, v0
	s_waitcnt lgkmcnt(0)
	v_pk_add_f32 v[0:1], v[0:1], v[2:3]
	ds_bpermute_b32 v3, v217, v1
	ds_bpermute_b32 v2, v217, v0
	s_waitcnt lgkmcnt(0)
	v_pk_add_f32 v[0:1], v[0:1], v[2:3]
	s_nop 0
	v_pk_fma_f32 v[0:1], v[0:1], s[4:5], v[64:65] op_sel_hi:[1,0,0]
	s_nop 0
	v_mul_f32_e32 v2, 0x4b800000, v1
	v_cmp_gt_f32_e64 s[0:1], s33, v1
	v_cmp_gt_f32_e32 vcc, s33, v0
	s_nop 0
	v_cndmask_b32_e64 v1, v1, v2, s[0:1]
	v_rsq_f32_e32 v1, v1
	s_nop 0
	v_mul_f32_e32 v2, 0x45800000, v1
	v_cndmask_b32_e64 v1, v1, v2, s[0:1]
	v_mul_f32_e32 v2, v60, v1
	v_mul_f32_e32 v2, v72, v2
	v_bfe_u32 v3, v2, 16, 1
	v_add3_u32 v2, v2, v3, s2
	ds_write_b16_d16_hi v73, v2 offset:6528
	v_mul_f32_e32 v2, v44, v1
	v_mul_f32_e32 v2, v71, v2
	v_bfe_u32 v3, v2, 16, 1
	v_add3_u32 v2, v2, v3, s2
	ds_write_b16_d16_hi v73, v2 offset:6592
	v_mul_f32_e32 v2, v12, v1
	v_mul_f32_e32 v2, v70, v2
	v_bfe_u32 v3, v2, 16, 1
	v_mul_f32_e32 v1, v28, v1
	v_add3_u32 v2, v2, v3, s2
	v_mul_f32_e32 v1, v69, v1
	ds_write_b16_d16_hi v73, v2 offset:6656
	v_bfe_u32 v2, v1, 16, 1
	v_add3_u32 v1, v1, v2, s2
	ds_write_b16_d16_hi v73, v1 offset:6720
	v_mul_f32_e32 v1, 0x4b800000, v0
	v_cndmask_b32_e32 v0, v0, v1, vcc
	v_rsq_f32_e32 v0, v0
	v_mov_b32_e32 v3, v14
	v_mul_f32_e32 v1, 0x45800000, v0
	v_cndmask_b32_e32 v0, v0, v1, vcc
	v_mul_f32_e32 v1, v61, v0
	v_mul_f32_e32 v1, v72, v1
	v_bfe_u32 v2, v1, 16, 1
	v_add3_u32 v1, v1, v2, s2
	ds_write_b16_d16_hi v73, v1 offset:6800
	v_mul_f32_e32 v1, v45, v0
	v_mul_f32_e32 v1, v71, v1
	v_bfe_u32 v2, v1, 16, 1
	v_add3_u32 v1, v1, v2, s2
	ds_write_b16_d16_hi v73, v1 offset:6864
	v_mul_f32_e32 v1, v13, v0
	v_mul_f32_e32 v1, v70, v1
	v_bfe_u32 v2, v1, 16, 1
	v_mul_f32_e32 v0, v29, v0
	v_add3_u32 v1, v1, v2, s2
	v_mul_f32_e32 v0, v69, v0
	ds_write_b16_d16_hi v73, v1 offset:6928
	v_bfe_u32 v1, v0, 16, 1
	v_add3_u32 v0, v0, v1, s2
	ds_write_b16_d16_hi v73, v0 offset:6992
	v_mov_b32_e32 v0, v46
	v_mov_b32_e32 v1, v62
	v_pk_mul_f32 v[0:1], v[0:1], v[0:1]
	v_mov_b32_e32 v2, v30
	v_pk_mul_f32 v[2:3], v[2:3], v[2:3]
	v_mov_b32_e32 v9, v0
	v_mov_b32_e32 v0, v5
	v_pk_add_f32 v[0:1], v[8:9], v[0:1]
	v_mov_b32_e32 v5, v3
	v_pk_add_f32 v[0:1], v[4:5], v[0:1]
	v_mov_b32_e32 v7, v2
	v_pk_add_f32 v[0:1], v[6:7], v[0:1]
	ds_bpermute_b32 v3, v221, v1
	ds_bpermute_b32 v2, v221, v0
	v_bfe_u32 v6, v66, 4, 2
	v_lshl_add_u32 v7, v67, 5, s74
	s_waitcnt lgkmcnt(0)
	v_pk_add_f32 v[0:1], v[0:1], v[2:3]
	ds_bpermute_b32 v3, v220, v1
	ds_bpermute_b32 v2, v220, v0
	s_waitcnt lgkmcnt(0)
	v_pk_add_f32 v[0:1], v[0:1], v[2:3]
	ds_bpermute_b32 v3, v219, v1
	ds_bpermute_b32 v2, v219, v0
	s_waitcnt lgkmcnt(0)
; DEV bf16_t f2bf(float f) { unsigned u = __float_as_uint(f); u += 0x7fffu + ((u >> 16) & 1u); return (bf16_t)(u >> 16); }
; DEV int lv(int x) { asm volatile("" : "+v"(x)); return x; }
; DEV int crow(int r, int hi) { return (r & 3) + 8 * (r >> 2) + 4 * hi; }
; DEV void diff16_pass(const bf16_t* __restrict__ proj, int qcol, int kcol, int vcol, int q0, f32x4 (&o)[2][8], f32x4 (&l_out)[2], unsigned char* lds) {
;   const int tid = lv(threadIdx.x), wid = tid >> 6, lane = tid & 63, fr = lane & 15, fq = lane >> 4;
;   float* al_l = (float*)(lds + D_WSF) + wid * 64 + 32;
;   const lds_cptr qrd = (lds_cptr)shm_raw + D_QOFF + wid * 4096 + lane * 16;
; #pragma unroll
;   for (int g = 0; g < 2; ++g) { const int sl = 16 * g + fr; const bf16_t* Qw = proj + (size_t)(q0 + 64 * (sl >> 3) + 8 * wid + (sl & 7)) * INW + qcol + fq * 8;
;     *reinterpret_cast<bf16x8*>(lds + D_QOFF + wid * 4096 + (g * 2 + 0) * 1024 + lane * 16) = *reinterpret_cast<const bf16x8*>(Qw);
;     *reinterpret_cast<bf16x8*>(lds + D_QOFF + wid * 4096 + (g * 2 + 1) * 1024 + lane * 16) = *reinterpret_cast<const bf16x8*>(Qw + 32); }
; template <bool SPREAD>
; DEV void attn_store(f32x16 (&o)[4], const float* __restrict__ gain, float oscale, bf16_t* __restrict__ mix, int q0, int colbase) {
;     ...
;   for (int r = 0; r < 16; ++r) {
;     float ss = o[0][r] * o[0][r] + o[1][r] * o[1][r] + o[2][r] * o[2][r] + o[3][r] * o[3][r];
;     ss += __shfl_xor(ss, 1); ss += __shfl_xor(ss, 2); ss += __shfl_xor(ss, 4); ss += __shfl_xor(ss, 8); ss += __shfl_xor(ss, 16);
;     const float rn = rsqrtf(ss * (1.f / 128.f) + EPS);
;     const int cr = crow(r, hi);
; #pragma unroll
;     for (int d = 0; d < 4; ++d) *reinterpret_cast<bf16_t*>(sc + cr * 272 + (d * 32 + r32) * 2) = f2bf(o[d][r] * rn * gn[d]);
;   }
; #pragma unroll
;   for (int i = 0; i < 8; ++i) { const int rs = 4 * i + (lane >> 4);
;     const u32x4 w = *reinterpret_cast<const u32x4*>(sc + rs * 272 + (lane & 15) * 16);
;     const size_t row = SPREAD ? (size_t)(q0 + 64 * (rs >> 3) + 8 * wid + (rs & 7)) : (size_t)(q0 + wid * 32 + rs);
;     *reinterpret_cast<u32x4*>(mix + row * DM + colbase + (lane & 15) * 8) = w; }
;   __syncthreads();
	v_pk_add_f32 v[0:1], v[0:1], v[2:3]
	ds_bpermute_b32 v3, v218, v1
	ds_bpermute_b32 v2, v218, v0
	s_waitcnt lgkmcnt(0)
	v_pk_add_f32 v[0:1], v[0:1], v[2:3]
	ds_bpermute_b32 v3, v217, v1
	ds_bpermute_b32 v2, v217, v0
	s_waitcnt lgkmcnt(0)
	v_pk_add_f32 v[0:1], v[0:1], v[2:3]
	s_nop 0
	v_pk_fma_f32 v[0:1], v[0:1], s[4:5], v[64:65] op_sel_hi:[1,0,0]
	s_nop 0
	v_mul_f32_e32 v2, 0x4b800000, v1
	v_cmp_gt_f32_e64 s[0:1], s33, v1
	v_cmp_gt_f32_e32 vcc, s33, v0
	s_nop 0
	v_cndmask_b32_e64 v1, v1, v2, s[0:1]
	v_rsq_f32_e32 v1, v1
	s_nop 0
	v_mul_f32_e32 v2, 0x45800000, v1
	v_cndmask_b32_e64 v1, v1, v2, s[0:1]
	v_mul_f32_e32 v2, v62, v1
	v_mul_f32_e32 v2, v72, v2
	v_bfe_u32 v3, v2, 16, 1
	v_add3_u32 v2, v2, v3, s2
	ds_write_b16_d16_hi v73, v2 offset:7072
	v_mul_f32_e32 v2, v46, v1
	v_mul_f32_e32 v2, v71, v2
	v_bfe_u32 v3, v2, 16, 1
	v_add3_u32 v2, v2, v3, s2
	ds_write_b16_d16_hi v73, v2 offset:7136
	v_mul_f32_e32 v2, v14, v1
	v_mul_f32_e32 v2, v70, v2
	v_bfe_u32 v3, v2, 16, 1
	v_mul_f32_e32 v1, v30, v1
	v_add3_u32 v2, v2, v3, s2
	v_mul_f32_e32 v1, v69, v1
	ds_write_b16_d16_hi v73, v2 offset:7200
	v_bfe_u32 v2, v1, 16, 1
	v_add3_u32 v1, v1, v2, s2
	ds_write_b16_d16_hi v73, v1 offset:7264
	v_mul_f32_e32 v1, 0x4b800000, v0
	v_cndmask_b32_e32 v0, v0, v1, vcc
	v_rsq_f32_e32 v0, v0
	v_readlane_b32 s0, v255, 47
	v_readlane_b32 s1, v255, 48
	v_mul_f32_e32 v1, 0x45800000, v0
	v_cndmask_b32_e32 v0, v0, v1, vcc
	v_mul_f32_e32 v1, v63, v0
	v_mul_f32_e32 v1, v72, v1
	v_bfe_u32 v2, v1, 16, 1
	v_add3_u32 v1, v1, v2, s2
	ds_write_b16_d16_hi v73, v1 offset:7344
	v_mul_f32_e32 v1, v47, v0
	v_mul_f32_e32 v1, v71, v1
	v_bfe_u32 v2, v1, 16, 1
	v_add3_u32 v1, v1, v2, s2
	ds_write_b16_d16_hi v73, v1 offset:7408
	v_mul_f32_e32 v1, v15, v0
	v_mul_f32_e32 v1, v70, v1
	v_bfe_u32 v2, v1, 16, 1
	v_mul_f32_e32 v0, v31, v0
	v_add3_u32 v1, v1, v2, s2
	v_mul_f32_e32 v0, v69, v0
	ds_write_b16_d16_hi v73, v1 offset:7472
	v_bfe_u32 v1, v0, 16, 1
	v_add3_u32 v0, v0, v1, s2
	ds_write_b16_d16_hi v73, v0 offset:7536
	v_lshlrev_b32_e32 v0, 4, v66
	v_and_b32_e32 v192, 0xf0, v0
	v_mul_u32_u24_e32 v0, 0x110, v6
	v_add3_u32 v10, v68, v192, v0
	ds_read_b128 v[0:3], v10
	v_or_b32_e32 v6, v7, v6
	v_ashrrev_i32_e32 v7, 31, v6
	v_lshl_add_u64 v[4:5], s[0:1], 0, v[192:193]
	v_lshlrev_b64 v[8:9], 12, v[6:7]
	v_lshl_add_u64 v[8:9], v[4:5], 0, v[8:9]
	s_waitcnt lgkmcnt(0)
	global_store_dwordx4 v[8:9], v[0:3], off
	ds_read_b128 v[0:3], v10 offset:1088
	v_or_b32_e32 v8, 4, v6
	v_ashrrev_i32_e32 v9, 31, v8
	v_lshlrev_b64 v[8:9], 12, v[8:9]
	v_lshl_add_u64 v[8:9], v[4:5], 0, v[8:9]
	s_waitcnt lgkmcnt(0)
	global_store_dwordx4 v[8:9], v[0:3], off
	ds_read_b128 v[0:3], v10 offset:2176
	v_or_b32_e32 v8, 8, v6
	v_ashrrev_i32_e32 v9, 31, v8
	v_lshlrev_b64 v[8:9], 12, v[8:9]
	v_lshl_add_u64 v[8:9], v[4:5], 0, v[8:9]
	s_waitcnt lgkmcnt(0)
	global_store_dwordx4 v[8:9], v[0:3], off
	ds_read_b128 v[0:3], v10 offset:3264
	v_or_b32_e32 v8, 12, v6
	v_ashrrev_i32_e32 v9, 31, v8
	v_lshlrev_b64 v[8:9], 12, v[8:9]
	v_lshl_add_u64 v[8:9], v[4:5], 0, v[8:9]
	s_waitcnt lgkmcnt(0)
	global_store_dwordx4 v[8:9], v[0:3], off
	ds_read_b128 v[0:3], v10 offset:4352
	v_or_b32_e32 v8, 16, v6
	v_ashrrev_i32_e32 v9, 31, v8
	v_lshlrev_b64 v[8:9], 12, v[8:9]
	v_lshl_add_u64 v[8:9], v[4:5], 0, v[8:9]
	s_waitcnt lgkmcnt(0)
	global_store_dwordx4 v[8:9], v[0:3], off
	ds_read_b128 v[0:3], v10 offset:5440
	v_or_b32_e32 v8, 20, v6
	v_ashrrev_i32_e32 v9, 31, v8
	v_lshlrev_b64 v[8:9], 12, v[8:9]
	v_lshl_add_u64 v[8:9], v[4:5], 0, v[8:9]
	s_waitcnt lgkmcnt(0)
	global_store_dwordx4 v[8:9], v[0:3], off
	ds_read_b128 v[0:3], v10 offset:6528
	v_or_b32_e32 v8, 24, v6
	v_ashrrev_i32_e32 v9, 31, v8
	v_lshlrev_b64 v[8:9], 12, v[8:9]
	v_lshl_add_u64 v[8:9], v[4:5], 0, v[8:9]
	s_waitcnt lgkmcnt(0)
	global_store_dwordx4 v[8:9], v[0:3], off
	ds_read_b128 v[0:3], v10 offset:7616
	v_or_b32_e32 v6, 28, v6
	v_ashrrev_i32_e32 v7, 31, v6
	v_lshlrev_b64 v[6:7], 12, v[6:7]
	v_lshl_add_u64 v[4:5], v[4:5], 0, v[6:7]
	v_mov_b32_e32 v8, v210
	s_waitcnt lgkmcnt(0)
	global_store_dwordx4 v[4:5], v[0:3], off
	s_barrier
	v_readlane_b32 s0, v255, 51
	v_ashrrev_i32_e32 v9, 6, v8
	v_and_b32_e32 v0, 0x3fffffc0, v8
	v_lshlrev_b32_e32 v12, 3, v8
	v_and_b32_e32 v13, 7, v8
	v_lshl_add_u32 v225, v0, 2, s16
	v_and_b32_e32 v0, 64, v12
	v_lshlrev_b32_e32 v1, 3, v9
	v_or_b32_e32 v2, s74, v13
	v_and_b32_e32 v192, 48, v8
	v_readlane_b32 s1, v255, 52
	v_add3_u32 v14, v2, v1, v0
	v_and_b32_e32 v227, 63, v8
	v_lshl_add_u64 v[4:5], s[0:1], 0, v[192:193]
	v_readlane_b32 s0, v255, 10
	v_lshlrev_b32_e32 v11, 4, v227
	v_bfe_u32 v10, v8, 4, 2
	v_lshl_add_u32 v15, v9, 12, s0
	v_mad_i64_i32 v[6:7], s[0:1], v14, s85, v[4:5]
	global_load_dwordx4 v[0:3], v[6:7], off
	global_load_dwordx4 v[96:99], v[6:7], off offset:64
	v_add_u32_e32 v108, 0x80, v14
	v_mad_i64_i32 v[4:5], s[0:1], v108, s85, v[4:5]
	global_load_dwordx4 v[100:103], v[4:5], off
	global_load_dwordx4 v[104:107], v[4:5], off offset:64
	v_add_u32_e32 v228, v15, v11
	v_lshrrev_b32_e32 v15, 6, v8
	v_and_b32_e32 v15, 4, v15
	v_lshl_add_u32 v17, v8, 4, v17
	v_lshrrev_b32_e32 v17, 8, v17
	v_and_b32_e32 v226, 15, v8
	s_waitcnt vmcnt(0)
; DEV void diff16_pass(const bf16_t* __restrict__ proj, int qcol, int kcol, int vcol, int q0, f32x4 (&o)[2][8], f32x4 (&l_out)[2], unsigned char* lds) {
;     ...
;   for (int g = 0; g < 2; ++g) { const int sl = 16 * g + fr; const bf16_t* Qw = proj + (size_t)(q0 + 64 * (sl >> 3) + 8 * wid + (sl & 7)) * INW + qcol + fq * 8;
;     *reinterpret_cast<bf16x8*>(lds + D_QOFF + wid * 4096 + (g * 2 + 0) * 1024 + lane * 16) = *reinterpret_cast<const bf16x8*>(Qw);
;     *reinterpret_cast<bf16x8*>(lds + D_QOFF + wid * 4096 + (g * 2 + 1) * 1024 + lane * 16) = *reinterpret_cast<const bf16x8*>(Qw + 32); }
;   const int c0 = q0 >> 6, NT = c0 + 4, lim0 = c0 + (fr >> 3), lim1 = c0 + 2 + (fr >> 3);
;   const int kf = ((fr >> 1) & 1) | ((fr >> 2) << 1);
;   const lds_cptr krd = (lds_cptr)shm_raw + D_KOFF + (8 * (fr >> 2) + (fr & 3)) * 128;
;   const int kch0 = ((0 + fq) ^ kf) << 4, kch1 = ((4 + fq) ^ kf) << 4;
;   const int vlane = (fq >> 1) * 512 + (fq & 1) * 256 + (fr >> 2) * 64 + (fr & 3) * 8;
;   const lds_cptr vrdE = (lds_cptr)shm_raw + vlane + (fq & 1) * 32, vrdO = (lds_cptr)shm_raw + vlane + (1 - (fq & 1)) * 32;
;   typedef unsigned char __attribute__((address_space(3))) lds_u8w;
;   lds_u8w* ldsw = (lds_u8w*)shm_raw;
;   unsigned Kg, Vg0, Vg1;
;   { const int r = tid >> 3, fK = ((r >> 1) & 1) | (((r >> 3) & 3) << 1); Kg = (unsigned)(r * INW + kcol + (((tid & 7) ^ fK) * 8)) * 2u;
;     ...
;     VSRC(tid, Vg0); VSRC(512 + tid, Vg1);
;     ...
;   }
;   const unsigned dmaw = (unsigned)__builtin_amdgcn_readfirstlane(wid) * 1024u;
	ds_write_b128 v228, v[0:3]
	ds_write_b128 v228, v[96:99] offset:1024
	ds_write_b128 v228, v[100:103] offset:2048
	ds_write_b128 v228, v[104:107] offset:3072
	v_or_b32_e32 v6, 4, v10
	s_movk_i32 s0, 0x1800
	v_lshrrev_b32_e32 v14, 5, v8
	v_and_b32_e32 v14, 6, v14
	v_bfe_u32 v2, v8, 2, 2
	v_bfe_u32 v1, v8, 1, 1
	v_lshlrev_b32_e32 v3, 1, v2
	v_bitop3_b32 v5, v3, v10, v1 bitop3:0x36
	v_bitop3_b32 v1, v3, v6, v1 bitop3:0x36
	v_bfe_u32 v6, v227, 4, 1
	v_lshlrev_b32_e32 v7, 8, v6
	v_lshlrev_b32_e32 v48, 5, v6
	v_lshrrev_b32_e32 v6, 3, v8
	v_and_b32_e32 v3, 0x200, v11
	v_mul_lo_u32 v6, v6, s0
	v_readlane_b32 s0, v255, 49
	v_add3_u32 v3, 0, v3, v7
	v_lshrrev_b32_e32 v7, 4, v8
	v_bfe_u32 v11, v8, 4, 1
	v_add_lshl_u32 v6, s0, v6, 1
	s_mov_b32 s0, 0x1fffe0
	v_bitop3_b32 v11, v11, v13, v14 bitop3:0x36
	v_bfe_u32 v13, v8, 1, 27
	v_and_or_b32 v16, v7, s0, v15
	v_readlane_b32 s0, v255, 50
	v_xor_b32_e32 v7, v13, v7
	v_lshrrev_b32_e32 v0, 1, v8
	v_and_or_b32 v12, v12, 8, s0
	s_mov_b32 s0, 0xffffe0
	v_and_b32_e32 v14, 24, v13
	v_lshlrev_b32_e32 v7, 4, v7
	v_and_or_b32 v15, v17, s0, v15
	v_lshlrev_b32_e32 v4, 10, v2
	v_lshlrev_b32_e32 v10, 6, v2
	v_or3_b32 v16, v16, v2, v14
	v_and_b32_e32 v0, 0x60, v0
	v_and_b32_e32 v7, 16, v7
	v_or3_b32 v2, v15, v2, v14
	v_and_b32_e32 v13, 0x60, v13
	v_readfirstlane_b32 s0, v9
	v_mul_u32_u24_e32 v16, 0x1800, v16
	v_or3_b32 v0, v0, v7, v12
	v_mul_i32_i24_e32 v2, 0x1800, v2
	v_or3_b32 v7, v13, v7, v12
	v_and_b32_e32 v8, 3, v8
	s_lshl_b32 s0, s0, 10
	v_lshlrev_b32_e32 v231, 4, v1
	v_lshlrev_b32_e32 v1, 3, v8
	v_lshl_or_b32 v232, v11, 4, v6
	v_add_lshl_u32 v233, v0, v16, 1
	v_add_lshl_u32 v234, v7, v2, 1
	s_add_i32 s17, s15, s0
	v_add3_u32 v49, v3, v10, v1
	v_mov_b32_e32 v0, v233
	v_mov_b32_e32 v1, v232
	v_mov_b32_e32 v2, v234
	s_mov_b32 m0, s17
	s_add_i32 s18, s0, 0
	v_readlane_b32 s0, v253, 33
	global_load_lds_dwordx4 v1, s[86:87]
	s_mov_b32 m0, s18
	v_mov_b32_e32 v1, v232
	global_load_lds_dwordx4 v0, s[86:87]
	s_add_i32 m0, s18, 0x2000
	v_mov_b32_e32 v0, v233
	global_load_lds_dwordx4 v2, s[86:87]
	v_mov_b32_e32 v2, v234
	s_add_i32 m0, s18, 0x12000
	v_readlane_b32 s1, v253, 34
	v_lshlrev_b32_e32 v9, 7, v8
	v_add3_u32 v229, s15, v4, v9
	v_lshlrev_b32_e32 v230, 4, v5
	v_add_u32_e32 v50, v229, v230
	s_nop 0
	global_load_lds_dwordx4 v1, s[0:1]
	s_add_i32 m0, s18, 0x4000
	v_mov_b32_e32 v1, v232
	global_load_lds_dwordx4 v0, s[0:1]
	s_add_i32 m0, s18, 0x6000
	v_mov_b32_e32 v0, v233
	global_load_lds_dwordx4 v2, s[0:1]
	v_readlane_b32 s0, v253, 35
	v_mov_b32_e32 v2, v234
	s_add_i32 m0, s18, 0x14000
	v_readlane_b32 s1, v253, 36
	v_add_u32_e32 v51, v229, v231
	v_add_u32_e32 v223, v49, v48
	v_xad_u32 v224, v48, 32, v49
	s_nop 1
	global_load_lds_dwordx4 v1, s[0:1]
	s_add_i32 m0, s18, 0x8000
	s_nop 0
	global_load_lds_dwordx4 v0, s[0:1]
	s_add_i32 m0, s18, 0xa000
	s_cmp_gt_i32 s81, -1
	global_load_lds_dwordx4 v2, s[0:1]
	s_waitcnt vmcnt(3)
	s_waitcnt lgkmcnt(0)
	s_barrier
	ds_read_b128 v[24:27], v228
	ds_read_b128 v[28:31], v228 offset:1024
	ds_read_b128 v[32:35], v228 offset:2048
	ds_read_b128 v[36:39], v228 offset:3072
	ds_read_b128 v[0:3], v50
	ds_read_b128 v[4:7], v51
	s_waitcnt lgkmcnt(0)
	v_mfma_f32_16x16x32_bf16 v[8:11], v[0:3], v[24:27], 0
	s_cselect_b64 s[10:11], -1, 0
	s_cmp_lt_i32 s81, 0
	v_mfma_f32_16x16x32_bf16 v[12:15], v[0:3], v[32:35], 0
	v_mfma_f32_16x16x32_bf16 v[0:3], v[4:7], v[28:31], v[8:11]
	v_mfma_f32_16x16x32_bf16 v[4:7], v[4:7], v[36:39], v[12:15]
	s_nop 2
	ds_read_b128 v[8:11], v50 offset:512
	s_nop 1
	ds_read_b128 v[12:15], v51 offset:512
	s_waitcnt lgkmcnt(0)
	v_mfma_f32_16x16x32_bf16 v[16:19], v[8:11], v[24:27], 0
	v_mfma_f32_16x16x32_bf16 v[20:23], v[8:11], v[32:35], 0
	v_mfma_f32_16x16x32_bf16 v[8:11], v[12:15], v[28:31], v[16:19]
	v_mfma_f32_16x16x32_bf16 v[16:19], v[12:15], v[36:39], v[20:23]
	ds_read_b128 v[12:15], v50 offset:4096
	s_nop 4
	ds_read_b128 v[20:23], v51 offset:4096
	s_waitcnt lgkmcnt(0)
	v_mfma_f32_16x16x32_bf16 v[40:43], v[12:15], v[24:27], 0
	v_mfma_f32_16x16x32_bf16 v[44:47], v[12:15], v[32:35], 0
	v_mfma_f32_16x16x32_bf16 v[12:15], v[20:23], v[28:31], v[40:43]
	v_mfma_f32_16x16x32_bf16 v[20:23], v[20:23], v[36:39], v[44:47]
	s_nop 4
	ds_read_b128 v[40:43], v50 offset:4608
	ds_read_b128 v[44:47], v51 offset:4608
	s_waitcnt lgkmcnt(0)
	v_mfma_f32_16x16x32_bf16 v[24:27], v[40:43], v[24:27], 0
	v_mfma_f32_16x16x32_bf16 v[32:35], v[40:43], v[32:35], 0
	v_mfma_f32_16x16x32_bf16 v[24:27], v[44:47], v[28:31], v[24:27]
	v_mfma_f32_16x16x32_bf16 v[28:31], v[44:47], v[36:39], v[32:35]
	s_nop 5
	v_max_f32_e32 v32, v1, v1
	v_max_f32_e32 v33, v0, v0
	v_max_f32_e32 v32, v33, v32
	v_max_f32_e32 v33, v5, v5
	v_max_f32_e32 v34, v4, v4
	v_max_f32_e32 v33, v34, v33
	v_max3_f32 v32, v32, v2, v3
	v_max3_f32 v33, v33, v6, v7
	v_max3_f32 v32, v32, v8, v9
	v_max3_f32 v33, v33, v16, v17
	v_max3_f32 v32, v32, v10, v11
	v_max3_f32 v33, v33, v18, v19
	v_max3_f32 v32, v32, v12, v13
	v_max3_f32 v33, v33, v20, v21
	v_max3_f32 v32, v32, v14, v15
	v_max3_f32 v33, v33, v22, v23
	v_max3_f32 v32, v32, v24, v25
	v_max3_f32 v33, v33, v28, v29
	v_max3_f32 v32, v32, v26, v27
	v_max3_f32 v34, v33, v30, v31
	ds_bpermute_b32 v33, v217, v32
	ds_bpermute_b32 v35, v217, v34
	s_waitcnt lgkmcnt(0)
	v_max_f32_e32 v33, v33, v33
	v_max_f32_e32 v35, v35, v35
	v_max_f32_e32 v32, v32, v33
	v_max_f32_e32 v34, v34, v35
	ds_bpermute_b32 v33, v216, v32
	ds_bpermute_b32 v35, v216, v34
	s_cbranch_scc1 .LBB0_391
; #define VWAIT(n) asm volatile("s_waitcnt vmcnt(" #n ")" ::: "memory")
; #define LBAR() do { asm volatile("s_waitcnt lgkmcnt(0)" ::: "memory"); __builtin_amdgcn_s_barrier(); } while (0)
; #define VWAIT(n) asm volatile("s_waitcnt vmcnt(" #n ")" ::: "memory")
; #define LBAR() do { asm volatile("s_waitcnt lgkmcnt(0)" ::: "memory"); __builtin_amdgcn_s_barrier(); } while (0)
; #define ROWMAXF16(S, pm) do { _Pragma("unroll") for (int g = 0; g < 2; ++g) { float m_ = S[g][0][0]; \
;       _Pragma("unroll") for (int kb = 0; kb < 4; ++kb) _Pragma("unroll") for (int j = 0; j < 4; ++j) m_ = fmaxf(m_, S[g][kb][j]); pm[g] = m_; } } while (0)
; #define EXP16(S) do { _Pragma("unroll") for (int g = 0; g < 2; ++g) _Pragma("unroll") for (int kb = 0; kb < 4; ++kb) _Pragma("unroll") for (int j = 0; j < 4; ++j) S[g][kb][j] = __builtin_amdgcn_exp2f(S[g][kb][j]); } while (0)
; DEV void diff16_pass(const bf16_t* __restrict__ proj, int qcol, int kcol, int vcol, int q0, f32x4 (&o)[2][8], f32x4 (&l_out)[2], unsigned char* lds) {
;     ...
;   float m_reg[2] = {0.f, 0.f};
;   f32x4 ol[2] = {(f32x4){0.f, 0.f, 0.f, 0.f}, (f32x4){0.f, 0.f, 0.f, 0.f}};
;   const bf16x8 ones = {0x3F80, 0x3F80, 0x3F80, 0x3F80, 0x3F80, 0x3F80, 0x3F80, 0x3F80};
;   f32x4 negm[2] = {(f32x4){0.f, 0.f, 0.f, 0.f}, (f32x4){0.f, 0.f, 0.f, 0.f}};
; #pragma unroll
;   for (int g = 0; g < 2; ++g)
; #pragma unroll
;     for (int cb = 0; cb < 8; ++cb) o[g][cb] = (f32x4){0.f, 0.f, 0.f, 0.f};
;   f32x4 SA[2][4], SB2[2][4]; float alA[2], alB[2]; bool rfA = false, rfB = false; bf16x8 pa[2][2];
;   DMA(0); DMA(1); DMA(2); VWAIT(3); LBAR();
;   { QKT16(SA, 0); float pm_[2]; ROWMAXF16(SA, pm_); RESCALE16(SA, pm_, alA, rfA, true); alA[0] = 1.f; alA[1] = 1.f; rfA = false; EXP16(SA); }
	s_waitcnt lgkmcnt(0)
	v_max_f32_e32 v35, v35, v35
	v_max_f32_e32 v34, v34, v34
	v_max_f32_e32 v35, v34, v35
	v_sub_f32_e32 v5, v5, v35
	v_sub_f32_e32 v4, v4, v35
	v_exp_f32_e32 v137, v4
	v_exp_f32_e32 v148, v5
	v_max_f32_e32 v4, v33, v33
	v_max_f32_e32 v5, v32, v32
	v_sub_f32_e32 v7, v7, v35
	v_sub_f32_e32 v6, v6, v35
	v_max_f32_e32 v34, v5, v4
	v_exp_f32_e32 v149, v6
	v_exp_f32_e32 v151, v7
	v_sub_f32_e32 v4, v27, v34
	v_sub_f32_e32 v5, v26, v34
	v_sub_f32_e32 v6, v25, v34
	v_sub_f32_e32 v7, v24, v34
	v_exp_f32_e32 v152, v7
	v_exp_f32_e32 v154, v6
	v_exp_f32_e32 v155, v5
	v_exp_f32_e32 v157, v4
	v_sub_f32_e32 v4, v15, v34
	v_sub_f32_e32 v5, v14, v34
	v_sub_f32_e32 v6, v13, v34
	v_sub_f32_e32 v7, v12, v34
	v_sub_f32_e32 v31, v31, v35
	v_sub_f32_e32 v30, v30, v35
	v_sub_f32_e32 v29, v29, v35
	v_sub_f32_e32 v28, v28, v35
	v_sub_f32_e32 v23, v23, v35
	v_sub_f32_e32 v22, v22, v35
	v_sub_f32_e32 v21, v21, v35
	v_sub_f32_e32 v20, v20, v35
	v_sub_f32_e32 v19, v19, v35
	v_sub_f32_e32 v18, v18, v35
	v_sub_f32_e32 v17, v17, v35
	v_sub_f32_e32 v16, v16, v35
	v_exp_f32_e32 v153, v7
	v_exp_f32_e32 v156, v6
	v_exp_f32_e32 v158, v5
	v_exp_f32_e32 v159, v4
	v_sub_f32_e32 v4, v11, v34
	v_sub_f32_e32 v5, v10, v34
	v_sub_f32_e32 v6, v9, v34
	v_sub_f32_e32 v7, v8, v34
	v_sub_f32_e32 v3, v3, v34
	v_sub_f32_e32 v2, v2, v34
	v_sub_f32_e32 v1, v1, v34
	v_sub_f32_e32 v0, v0, v34
	v_exp_f32_e32 v128, v28
	v_exp_f32_e32 v130, v29
	v_exp_f32_e32 v131, v30
	v_exp_f32_e32 v133, v31
	v_exp_f32_e32 v129, v20
	v_exp_f32_e32 v134, v21
	v_exp_f32_e32 v135, v22
	v_exp_f32_e32 v138, v23
	v_exp_f32_e32 v132, v16
	v_exp_f32_e32 v136, v17
	v_exp_f32_e32 v139, v18
	v_exp_f32_e32 v150, v19
	v_exp_f32_e32 v240, v7
	v_exp_f32_e32 v242, v6
	v_exp_f32_e32 v243, v5
	v_exp_f32_e32 v246, v4
	v_exp_f32_e32 v241, v0
	v_exp_f32_e32 v244, v1
	v_exp_f32_e32 v245, v2
	v_exp_f32_e32 v247, v3
	v_lshrrev_b32_e32 v36, 3, v226
	v_pk_add_f32 v[208:209], v[34:35], 0 op_sel_hi:[1,0]
	v_mov_b32_e32 v2, v193
	v_mov_b32_e32 v3, v193
	v_or_b32_e32 v235, s75, v36
	v_xor_b32_e32 v76, 0x80000000, v209
	v_pk_add_f32 v[72:73], v[208:209], 0 neg_lo:[1,1] neg_hi:[1,1]
	v_mov_b32_e32 v0, v193
	v_mov_b32_e32 v1, v193
	v_mov_b64_e32 v[10:11], v[2:3]
	v_mov_b64_e32 v[26:27], v[2:3]
	v_mov_b64_e32 v[18:19], v[2:3]
	v_mov_b64_e32 v[38:39], v[2:3]
	v_mov_b64_e32 v[42:43], v[2:3]
	v_mov_b64_e32 v[50:51], v[2:3]
	v_mov_b64_e32 v[66:67], v[2:3]
	v_mov_b64_e32 v[6:7], v[2:3]
	v_mov_b64_e32 v[14:15], v[2:3]
	v_mov_b64_e32 v[30:31], v[2:3]
	v_mov_b64_e32 v[22:23], v[2:3]
	v_mov_b64_e32 v[34:35], v[2:3]
	v_mov_b64_e32 v[46:47], v[2:3]
	v_mov_b64_e32 v[54:55], v[2:3]
	v_mov_b64_e32 v[62:63], v[2:3]
	v_mov_b64_e32 v[70:71], v[2:3]
	v_mov_b64_e32 v[58:59], v[2:3]
	v_or_b32_e32 v236, 2, v235
	v_cmp_gt_u32_e64 s[4:5], 16, v227
	v_lshl_add_u32 v237, v226, 2, v225
	s_mov_b32 s23, 1
	s_mov_b64 s[6:7], 0
	v_mov_b32_e32 v249, 1.0
	s_mov_b32 s19, 0x10000
	s_movk_i32 s20, 0x4000
	v_mov_b64_e32 v[8:9], v[0:1]
	v_mov_b64_e32 v[24:25], v[0:1]
	v_mov_b64_e32 v[16:17], v[0:1]
	v_mov_b64_e32 v[36:37], v[0:1]
	v_mov_b64_e32 v[40:41], v[0:1]
	v_mov_b64_e32 v[48:49], v[0:1]
	v_mov_b64_e32 v[64:65], v[0:1]
	v_mov_b64_e32 v[4:5], v[0:1]
	v_mov_b64_e32 v[12:13], v[0:1]
	v_mov_b64_e32 v[28:29], v[0:1]
	v_mov_b64_e32 v[20:21], v[0:1]
	v_mov_b64_e32 v[32:33], v[0:1]
	v_mov_b64_e32 v[44:45], v[0:1]
	v_mov_b64_e32 v[52:53], v[0:1]
	v_mov_b64_e32 v[60:61], v[0:1]
	v_mov_b32_e32 v248, 1.0
	v_mov_b64_e32 v[68:69], v[0:1]
	v_mov_b64_e32 v[56:57], v[0:1]
	v_mov_b32_e32 v73, v72
	v_mov_b32_e32 v74, v72
	v_mov_b32_e32 v75, v72
	v_mov_b32_e32 v77, v76
	v_mov_b32_e32 v78, v76
	v_mov_b32_e32 v79, v76
	s_cmp_lt_u32 s18, 0x1000
	s_cbranch_scc0 .Lprio_a
	s_setprio 1

; DEV unsigned cvtpk(float lo, float hi) { f32x2_t v = {lo, hi}; bf16x2_t b = __builtin_convertvector(v, bf16x2_t); return __builtin_bit_cast(unsigned, b); }
; DEV void attn_phase(const Params& p, int layer) {
;     ...
;         for (int g = 0; g < 2; ++g) { const f32x4 l4 = ld[g];
;           const f32x4 il = {__builtin_amdgcn_rcpf(l4[0]), __builtin_amdgcn_rcpf(l4[1]), __builtin_amdgcn_rcpf(l4[2]), __builtin_amdgcn_rcpf(l4[3])};
; #pragma unroll
;           for (int cb = 0; cb < 8; cb += 2) { const f32x4 a4 = od[g][cb] * il, b4 = od[g][cb + 1] * il;
;             const u32x4 w = {cvtpk(a4[0], a4[1]), cvtpk(a4[2], a4[3]), cvtpk(b4[0], b4[1]), cvtpk(b4[2], b4[3])};
;             *reinterpret_cast<u32x4*>((bf16_t*)o1s + (wid * 8 + g * 4 + (cb >> 1)) * 512 + lane * 8) = w; } }
.LBB0_393:
	v_cvt_pk_bf16_f32 v72, v162, v163
	v_cvt_pk_bf16_f32 v73, v161, v160
	v_cvt_pk_bf16_f32 v74, v167, v166
	v_cvt_pk_bf16_f32 v75, v164, v165
	v_cvt_pk_bf16_f32 v84, v175, v174
	v_cvt_pk_bf16_f32 v85, v172, v173
	v_cvt_pk_bf16_f32 v86, v183, v182
	v_cvt_pk_bf16_f32 v87, v181, v180
	s_mov_b32 s82, s80
	s_mov_b32 s83, s80
	s_mov_b32 s81, s80
	v_mov_b64_e32 v[94:95], s[82:83]
	v_cvt_pk_bf16_f32 v76, v171, v170
	v_cvt_pk_bf16_f32 v77, v169, v168
	v_cvt_pk_bf16_f32 v78, v178, v179
	v_cvt_pk_bf16_f32 v79, v177, v176
	v_cvt_pk_bf16_f32 v88, v186, v187
	v_cvt_pk_bf16_f32 v89, v185, v184
	v_cvt_pk_bf16_f32 v90, v191, v190
	v_cvt_pk_bf16_f32 v91, v189, v188
	v_mov_b64_e32 v[92:93], s[80:81]
	v_readlane_b32 s0, v255, 57
	v_readlane_b32 s1, v255, 58
	v_mfma_f32_16x16x32_bf16 v[68:71], v[72:75], v[92:95], v[68:71]
	s_andn2_b64 vcc, exec, s[10:11]
	v_mfma_f32_16x16x32_bf16 v[56:59], v[84:87], v[92:95], v[56:59]
	v_mfma_f32_16x16x32_bf16 v[80:83], v[76:79], v[92:95], v[68:71]
	v_mfma_f32_16x16x32_bf16 v[68:71], v[88:91], v[92:95], v[56:59]
	s_nop 5
	ds_read_b64_tr_b16 v[56:57], v223 offset:49152
	ds_read_b64_tr_b16 v[58:59], v223 offset:53248
	ds_read_b64_tr_b16 v[92:93], v223 offset:57344
	ds_read_b64_tr_b16 v[94:95], v223 offset:61440
	s_waitcnt lgkmcnt(0)
	v_mfma_f32_16x16x32_bf16 v[60:63], v[72:75], v[56:59], v[60:63]
	v_mfma_f32_16x16x32_bf16 v[56:59], v[84:87], v[56:59], v[64:67]
	v_mfma_f32_16x16x32_bf16 v[60:63], v[76:79], v[92:95], v[60:63]
	v_mfma_f32_16x16x32_bf16 v[56:59], v[88:91], v[92:95], v[56:59]
	s_nop 0
	ds_read_b64_tr_b16 v[64:65], v224 offset:49152
	ds_read_b64_tr_b16 v[66:67], v224 offset:53248
	ds_read_b64_tr_b16 v[92:93], v224 offset:57344
	ds_read_b64_tr_b16 v[94:95], v224 offset:61440
	s_waitcnt lgkmcnt(0)
	v_mfma_f32_16x16x32_bf16 v[52:55], v[72:75], v[64:67], v[52:55]
	v_mfma_f32_16x16x32_bf16 v[48:51], v[84:87], v[64:67], v[48:51]
	v_mfma_f32_16x16x32_bf16 v[52:55], v[76:79], v[92:95], v[52:55]
	v_mfma_f32_16x16x32_bf16 v[48:51], v[88:91], v[92:95], v[48:51]
	ds_read_b64_tr_b16 v[64:65], v223 offset:50176
	ds_read_b64_tr_b16 v[66:67], v223 offset:54272
	ds_read_b64_tr_b16 v[92:93], v223 offset:58368
	ds_read_b64_tr_b16 v[94:95], v223 offset:62464
	s_waitcnt lgkmcnt(0)
	v_mfma_f32_16x16x32_bf16 v[44:47], v[72:75], v[64:67], v[44:47]
	v_mfma_f32_16x16x32_bf16 v[40:43], v[84:87], v[64:67], v[40:43]
	v_mfma_f32_16x16x32_bf16 v[44:47], v[76:79], v[92:95], v[44:47]
	v_mfma_f32_16x16x32_bf16 v[40:43], v[88:91], v[92:95], v[40:43]
	ds_read_b64_tr_b16 v[64:65], v224 offset:50176
	ds_read_b64_tr_b16 v[66:67], v224 offset:54272
	ds_read_b64_tr_b16 v[92:93], v224 offset:58368
	ds_read_b64_tr_b16 v[94:95], v224 offset:62464
	s_waitcnt lgkmcnt(0)
	v_mfma_f32_16x16x32_bf16 v[32:35], v[72:75], v[64:67], v[32:35]
	v_mfma_f32_16x16x32_bf16 v[64:67], v[84:87], v[64:67], v[36:39]
	v_mfma_f32_16x16x32_bf16 v[36:39], v[76:79], v[92:95], v[32:35]
	v_mfma_f32_16x16x32_bf16 v[32:35], v[88:91], v[92:95], v[64:67]
	s_nop 5
	ds_read_b64_tr_b16 v[64:65], v223 offset:51200
	ds_read_b64_tr_b16 v[66:67], v223 offset:55296
	ds_read_b64_tr_b16 v[92:93], v223 offset:59392
	ds_read_b64_tr_b16 v[94:95], v223 offset:63488
	s_waitcnt lgkmcnt(0)
	v_mfma_f32_16x16x32_bf16 v[20:23], v[72:75], v[64:67], v[20:23]
	v_mfma_f32_16x16x32_bf16 v[16:19], v[84:87], v[64:67], v[16:19]
	v_mfma_f32_16x16x32_bf16 v[64:67], v[76:79], v[92:95], v[20:23]
	v_mfma_f32_16x16x32_bf16 v[16:19], v[88:91], v[92:95], v[16:19]
	s_nop 4
	ds_read_b64_tr_b16 v[20:21], v224 offset:51200
	ds_read_b64_tr_b16 v[22:23], v224 offset:55296
	ds_read_b64_tr_b16 v[92:93], v224 offset:59392
	ds_read_b64_tr_b16 v[94:95], v224 offset:63488
	s_waitcnt lgkmcnt(0)
	v_mfma_f32_16x16x32_bf16 v[28:31], v[72:75], v[20:23], v[28:31]
	v_mfma_f32_16x16x32_bf16 v[20:23], v[84:87], v[20:23], v[24:27]
	v_mfma_f32_16x16x32_bf16 v[24:27], v[76:79], v[92:95], v[28:31]
	v_mfma_f32_16x16x32_bf16 v[20:23], v[88:91], v[92:95], v[20:23]
	s_nop 4
	ds_read_b64_tr_b16 v[28:29], v223 offset:52224
	ds_read_b64_tr_b16 v[30:31], v223 offset:56320
	ds_read_b64_tr_b16 v[92:93], v223 offset:60416
	ds_read_b64_tr_b16 v[94:95], v223 offset:64512
	s_waitcnt lgkmcnt(0)
	v_mfma_f32_16x16x32_bf16 v[12:15], v[72:75], v[28:31], v[12:15]
	v_mfma_f32_16x16x32_bf16 v[8:11], v[84:87], v[28:31], v[8:11]
	v_mfma_f32_16x16x32_bf16 v[12:15], v[76:79], v[92:95], v[12:15]
	v_mfma_f32_16x16x32_bf16 v[8:11], v[88:91], v[92:95], v[8:11]
	ds_read_b64_tr_b16 v[28:29], v224 offset:52224
	ds_read_b64_tr_b16 v[30:31], v224 offset:56320
	ds_read_b64_tr_b16 v[92:93], v224 offset:60416
	ds_read_b64_tr_b16 v[94:95], v224 offset:64512
	s_waitcnt vmcnt(0)
	s_waitcnt lgkmcnt(0)
	s_waitcnt lgkmcnt(0)
	v_mfma_f32_16x16x32_bf16 v[4:7], v[72:75], v[28:31], v[4:7]
	v_rcp_f32_e32 v72, v80
	v_rcp_f32_e32 v73, v81
	v_rcp_f32_e32 v74, v82
	v_rcp_f32_e32 v75, v83
	v_mfma_f32_16x16x32_bf16 v[0:3], v[84:87], v[28:31], v[0:3]
	v_mul_f32_e64 v28, v72, v60
	v_mul_f32_e64 v29, v73, v61
	v_pk_mul_f32 v[52:53], v[72:73], v[52:53]
	v_pk_mul_f32 v[30:31], v[74:75], v[62:63]
	v_pk_mul_f32 v[54:55], v[74:75], v[54:55]
	v_cvt_pk_bf16_f32 v28, v28, v29
	v_cvt_pk_bf16_f32 v29, v30, v31
	v_cvt_pk_bf16_f32 v30, v52, v53
	v_cvt_pk_bf16_f32 v31, v54, v55
	v_mfma_f32_16x16x32_bf16 v[4:7], v[76:79], v[92:95], v[4:7]
	s_barrier
; DEV void diff16_pass(const bf16_t* __restrict__ proj, int qcol, int kcol, int vcol, int q0, f32x4 (&o)[2][8], f32x4 (&l_out)[2], unsigned char* lds) {
;   const int tid = lv(threadIdx.x), wid = tid >> 6, lane = tid & 63, fr = lane & 15, fq = lane >> 4;
;   float* al_l = (float*)(lds + D_WSF) + wid * 64 + 32;
;   const lds_cptr qrd = (lds_cptr)shm_raw + D_QOFF + wid * 4096 + lane * 16;
; #pragma unroll
;   for (int g = 0; g < 2; ++g) { const int sl = 16 * g + fr; const bf16_t* Qw = proj + (size_t)(q0 + 64 * (sl >> 3) + 8 * wid + (sl & 7)) * INW + qcol + fq * 8;
;     *reinterpret_cast<bf16x8*>(lds + D_QOFF + wid * 4096 + (g * 2 + 0) * 1024 + lane * 16) = *reinterpret_cast<const bf16x8*>(Qw);
;     *reinterpret_cast<bf16x8*>(lds + D_QOFF + wid * 4096 + (g * 2 + 1) * 1024 + lane * 16) = *reinterpret_cast<const bf16x8*>(Qw + 32); }
;   const int c0 = q0 >> 6, NT = c0 + 4, lim0 = c0 + (fr >> 3), lim1 = c0 + 2 + (fr >> 3);
;   const int kf = ((fr >> 1) & 1) | ((fr >> 2) << 1);
;   const lds_cptr krd = (lds_cptr)shm_raw + D_KOFF + (8 * (fr >> 2) + (fr & 3)) * 128;
;   const int kch0 = ((0 + fq) ^ kf) << 4, kch1 = ((4 + fq) ^ kf) << 4;
;   const int vlane = (fq >> 1) * 512 + (fq & 1) * 256 + (fr >> 2) * 64 + (fr & 3) * 8;
;   const lds_cptr vrdE = (lds_cptr)shm_raw + vlane + (fq & 1) * 32, vrdO = (lds_cptr)shm_raw + vlane + (1 - (fq & 1)) * 32;
;   typedef unsigned char __attribute__((address_space(3))) lds_u8w;
;   lds_u8w* ldsw = (lds_u8w*)shm_raw;
;   unsigned Kg, Vg0, Vg1;
;   { const int r = tid >> 3, fK = ((r >> 1) & 1) | (((r >> 3) & 3) << 1); Kg = (unsigned)(r * INW + kcol + (((tid & 7) ^ fK) * 8)) * 2u;
;     ...
;     VSRC(tid, Vg0); VSRC(512 + tid, Vg1);
;     ...
;   }
;   const unsigned dmaw = (unsigned)__builtin_amdgcn_readfirstlane(wid) * 1024u;
; DEV void attn_phase(const Params& p, int layer) {
;     ...
;         for (int g = 0; g < 2; ++g) { const f32x4 l4 = ld[g];
;           const f32x4 il = {__builtin_amdgcn_rcpf(l4[0]), __builtin_amdgcn_rcpf(l4[1]), __builtin_amdgcn_rcpf(l4[2]), __builtin_amdgcn_rcpf(l4[3])};
; #pragma unroll
;           for (int cb = 0; cb < 8; cb += 2) { const f32x4 a4 = od[g][cb] * il, b4 = od[g][cb + 1] * il;
;             const u32x4 w = {cvtpk(a4[0], a4[1]), cvtpk(a4[2], a4[3]), cvtpk(b4[0], b4[1]), cvtpk(b4[2], b4[3])};
;             *reinterpret_cast<u32x4*>((bf16_t*)o1s + (wid * 8 + g * 4 + (cb >> 1)) * 512 + lane * 8) = w; } }
	global_store_dwordx4 v[196:197], v[28:31], off
	v_pk_mul_f32 v[38:39], v[74:75], v[38:39]
	v_pk_mul_f32 v[36:37], v[72:73], v[36:37]
	v_pk_mul_f32 v[30:31], v[74:75], v[46:47]
	v_pk_mul_f32 v[28:29], v[72:73], v[44:45]
	v_pk_mul_f32 v[14:15], v[74:75], v[14:15]
	v_cvt_pk_bf16_f32 v28, v28, v29
	v_cvt_pk_bf16_f32 v29, v30, v31
	v_cvt_pk_bf16_f32 v30, v36, v37
	v_cvt_pk_bf16_f32 v31, v38, v39
	global_store_dwordx4 v[196:197], v[28:31], off offset:1024
	v_pk_mul_f32 v[36:37], v[74:75], v[26:27]
	v_pk_mul_f32 v[26:27], v[72:73], v[24:25]
	v_pk_mul_f32 v[28:29], v[74:75], v[66:67]
	v_pk_mul_f32 v[30:31], v[72:73], v[64:65]
	v_cvt_pk_bf16_f32 v25, v28, v29
	v_cvt_pk_bf16_f32 v24, v30, v31
	v_cvt_pk_bf16_f32 v26, v26, v27
	v_cvt_pk_bf16_f32 v27, v36, v37
	v_pk_mul_f32 v[12:13], v[72:73], v[12:13]
	global_store_dwordx4 v[196:197], v[24:27], off offset:2048
	v_mfma_f32_16x16x32_bf16 v[0:3], v[88:91], v[92:95], v[0:3]
	s_nop 0
	v_mul_f32_e64 v24, v74, v6
	v_mul_f32_e64 v25, v75, v7
	v_pk_mul_f32 v[6:7], v[72:73], v[4:5]
	v_cvt_pk_bf16_f32 v4, v12, v13
	v_cvt_pk_bf16_f32 v5, v14, v15
	v_rcp_f32_e32 v12, v68
	v_rcp_f32_e32 v13, v69
	v_rcp_f32_e32 v14, v70
	v_rcp_f32_e32 v15, v71
	v_cvt_pk_bf16_f32 v6, v6, v7
	v_cvt_pk_bf16_f32 v7, v24, v25
	global_store_dwordx4 v[196:197], v[4:7], off offset:3072
	v_pk_mul_f32 v[24:25], v[14:15], v[50:51]
	v_pk_mul_f32 v[26:27], v[12:13], v[48:49]
	v_pk_mul_f32 v[6:7], v[14:15], v[58:59]
	v_pk_mul_f32 v[4:5], v[12:13], v[56:57]
	s_nop 0
	v_cvt_pk_bf16_f32 v4, v4, v5
	v_cvt_pk_bf16_f32 v5, v6, v7
	v_cvt_pk_bf16_f32 v6, v26, v27
	v_cvt_pk_bf16_f32 v7, v24, v25
	global_store_dwordx4 v[198:199], v[4:7], off
	v_pk_mul_f32 v[24:25], v[14:15], v[34:35]
	v_pk_mul_f32 v[26:27], v[12:13], v[32:33]
	v_pk_mul_f32 v[6:7], v[14:15], v[42:43]
	v_pk_mul_f32 v[4:5], v[12:13], v[40:41]
	s_nop 0
	v_cvt_pk_bf16_f32 v4, v4, v5
	v_cvt_pk_bf16_f32 v5, v6, v7
	v_cvt_pk_bf16_f32 v6, v26, v27
	v_cvt_pk_bf16_f32 v7, v24, v25
	global_store_dwordx4 v[200:201], v[4:7], off
	s_nop 1
	v_pk_mul_f32 v[6:7], v[14:15], v[18:19]
	v_pk_mul_f32 v[4:5], v[12:13], v[16:17]
	v_pk_mul_f32 v[16:17], v[14:15], v[22:23]
	v_pk_mul_f32 v[18:19], v[12:13], v[20:21]
	v_cvt_pk_bf16_f32 v4, v4, v5
	v_cvt_pk_bf16_f32 v5, v6, v7
	v_cvt_pk_bf16_f32 v6, v18, v19
	v_cvt_pk_bf16_f32 v7, v16, v17
	global_store_dwordx4 v[202:203], v[4:7], off
	v_mov_b32_e32 v17, 0x2000
	s_nop 0
	v_pk_mul_f32 v[4:5], v[14:15], v[10:11]
	v_pk_mul_f32 v[6:7], v[12:13], v[8:9]
	v_pk_mul_f32 v[8:9], v[14:15], v[2:3]
	v_pk_mul_f32 v[2:3], v[12:13], v[0:1]
	v_cvt_pk_bf16_f32 v0, v6, v7
	v_cvt_pk_bf16_f32 v1, v4, v5
	v_cvt_pk_bf16_f32 v2, v2, v3
	v_cvt_pk_bf16_f32 v3, v8, v9
	v_mov_b32_e32 v8, v210
	global_store_dwordx4 v[204:205], v[0:3], off
	s_nop 0
	v_ashrrev_i32_e32 v9, 6, v8
	v_and_b32_e32 v0, 0x3fffffc0, v8
	v_lshlrev_b32_e32 v12, 3, v8
	v_and_b32_e32 v13, 7, v8
	v_lshl_add_u32 v225, v0, 2, s16
	v_and_b32_e32 v0, 64, v12
	v_lshlrev_b32_e32 v1, 3, v9
	v_or_b32_e32 v2, s74, v13
	v_and_b32_e32 v192, 48, v8
	v_add3_u32 v14, v2, v1, v0
	v_lshl_add_u64 v[4:5], s[0:1], 0, v[192:193]
	v_readlane_b32 s0, v255, 10
	v_and_b32_e32 v227, 63, v8
	v_lshlrev_b32_e32 v11, 4, v227
	v_lshl_add_u32 v15, v9, 12, s0
	v_mad_i64_i32 v[6:7], s[0:1], v14, s85, v[4:5]
	global_load_dwordx4 v[0:3], v[6:7], off
	global_load_dwordx4 v[96:99], v[6:7], off offset:64
	v_add_u32_e32 v108, 0x80, v14
	v_mad_i64_i32 v[4:5], s[0:1], v108, s85, v[4:5]
	global_load_dwordx4 v[100:103], v[4:5], off
	global_load_dwordx4 v[104:107], v[4:5], off offset:64
	v_add_u32_e32 v228, v15, v11
	v_bfe_u32 v10, v8, 4, 2
	v_lshrrev_b32_e32 v15, 6, v8
	v_and_b32_e32 v15, 4, v15
	v_lshl_add_u32 v17, v8, 4, v17
	v_lshrrev_b32_e32 v17, 8, v17
	v_and_b32_e32 v226, 15, v8
	s_waitcnt vmcnt(0)
	ds_write_b128 v228, v[0:3]
	ds_write_b128 v228, v[96:99] offset:1024
	ds_write_b128 v228, v[100:103] offset:2048
	ds_write_b128 v228, v[104:107] offset:3072
	v_or_b32_e32 v6, 4, v10
	s_movk_i32 s0, 0x1800
	v_lshrrev_b32_e32 v14, 5, v8
	v_and_b32_e32 v14, 6, v14
	v_bfe_u32 v2, v8, 2, 2
	v_bfe_u32 v1, v8, 1, 1
	v_lshlrev_b32_e32 v3, 1, v2
	v_bitop3_b32 v5, v3, v10, v1 bitop3:0x36
	v_bitop3_b32 v1, v3, v6, v1 bitop3:0x36
	v_bfe_u32 v6, v227, 4, 1
	v_lshlrev_b32_e32 v7, 8, v6
	v_lshlrev_b32_e32 v48, 5, v6
	v_lshrrev_b32_e32 v6, 3, v8
	v_and_b32_e32 v3, 0x200, v11
	v_mul_lo_u32 v6, v6, s0
	v_readlane_b32 s0, v255, 54
	v_add3_u32 v3, 0, v3, v7
	v_lshrrev_b32_e32 v7, 4, v8
	v_bfe_u32 v11, v8, 4, 1
	v_add_lshl_u32 v6, s0, v6, 1
	s_mov_b32 s0, 0x1fffe0
	v_bitop3_b32 v11, v11, v13, v14 bitop3:0x36
	v_bfe_u32 v13, v8, 1, 27
	v_and_or_b32 v16, v7, s0, v15
	v_readlane_b32 s0, v255, 50
	v_xor_b32_e32 v7, v13, v7
	v_lshrrev_b32_e32 v0, 1, v8
	v_and_or_b32 v12, v12, 8, s0
	s_mov_b32 s0, 0xffffe0
	v_and_b32_e32 v14, 24, v13
	v_lshlrev_b32_e32 v7, 4, v7
	v_and_or_b32 v15, v17, s0, v15
	v_lshlrev_b32_e32 v4, 10, v2
	v_lshlrev_b32_e32 v10, 6, v2
	v_or3_b32 v16, v16, v2, v14
	v_and_b32_e32 v0, 0x60, v0
	v_and_b32_e32 v7, 16, v7
	v_or3_b32 v2, v15, v2, v14
	v_and_b32_e32 v13, 0x60, v13
	v_readfirstlane_b32 s0, v9
	v_mul_u32_u24_e32 v16, 0x1800, v16
	v_or3_b32 v0, v0, v7, v12
	v_mul_i32_i24_e32 v2, 0x1800, v2
	v_or3_b32 v7, v13, v7, v12
	v_and_b32_e32 v8, 3, v8
	s_lshl_b32 s0, s0, 10
	v_lshlrev_b32_e32 v231, 4, v1
	v_lshlrev_b32_e32 v1, 3, v8
	v_lshl_or_b32 v232, v11, 4, v6
	v_add_lshl_u32 v233, v0, v16, 1
	v_add_lshl_u32 v234, v7, v2, 1
	s_add_i32 s12, s15, s0
	v_add3_u32 v49, v3, v10, v1
	v_mov_b32_e32 v0, v233
	v_mov_b32_e32 v1, v232
	v_mov_b32_e32 v2, v234
	s_mov_b32 m0, s12
	s_add_i32 s13, s0, 0
	v_readlane_b32 s0, v253, 33
	global_load_lds_dwordx4 v1, s[86:87]
	s_mov_b32 m0, s13
	v_mov_b32_e32 v1, v232
	global_load_lds_dwordx4 v0, s[86:87]
	s_add_i32 m0, s13, 0x2000
	v_mov_b32_e32 v0, v233
	global_load_lds_dwordx4 v2, s[86:87]
	v_mov_b32_e32 v2, v234
	s_add_i32 m0, s13, 0x12000
	v_readlane_b32 s1, v253, 34
	v_lshlrev_b32_e32 v9, 7, v8
	v_add3_u32 v229, s15, v4, v9
	v_lshlrev_b32_e32 v230, 4, v5
	v_add_u32_e32 v50, v229, v230
	s_nop 0
	global_load_lds_dwordx4 v1, s[0:1]
	s_add_i32 m0, s13, 0x4000
	v_mov_b32_e32 v1, v234
	global_load_lds_dwordx4 v0, s[0:1]
	s_add_i32 m0, s13, 0x6000
	v_mov_b32_e32 v0, v232
	global_load_lds_dwordx4 v2, s[0:1]
	v_readlane_b32 s0, v253, 35
	v_mov_b32_e32 v2, v233
	s_add_i32 m0, s13, 0x14000
	v_readlane_b32 s1, v253, 36
	v_add_u32_e32 v51, v229, v231
	v_add_u32_e32 v223, v49, v48
	v_xad_u32 v224, v48, 32, v49
	s_nop 1
	global_load_lds_dwordx4 v0, s[0:1]
	s_add_i32 m0, s13, 0x8000
	s_nop 0
	global_load_lds_dwordx4 v2, s[0:1]
	s_add_i32 m0, s13, 0xa000
	s_nop 0
	global_load_lds_dwordx4 v1, s[0:1]
	s_waitcnt vmcnt(3)
	s_waitcnt lgkmcnt(0)
	s_barrier
; #define VWAIT(n) asm volatile("s_waitcnt vmcnt(" #n ")" ::: "memory")
; #define LBAR() do { asm volatile("s_waitcnt lgkmcnt(0)" ::: "memory"); __builtin_amdgcn_s_barrier(); } while (0)
; #define VWAIT(n) asm volatile("s_waitcnt vmcnt(" #n ")" ::: "memory")
; #define LBAR() do { asm volatile("s_waitcnt lgkmcnt(0)" ::: "memory"); __builtin_amdgcn_s_barrier(); } while (0)
; #define ROWMAXF16(S, pm) do { _Pragma("unroll") for (int g = 0; g < 2; ++g) { float m_ = S[g][0][0]; \
;       _Pragma("unroll") for (int kb = 0; kb < 4; ++kb) _Pragma("unroll") for (int j = 0; j < 4; ++j) m_ = fmaxf(m_, S[g][kb][j]); pm[g] = m_; } } while (0)
; #define EXP16(S) do { _Pragma("unroll") for (int g = 0; g < 2; ++g) _Pragma("unroll") for (int kb = 0; kb < 4; ++kb) _Pragma("unroll") for (int j = 0; j < 4; ++j) S[g][kb][j] = __builtin_amdgcn_exp2f(S[g][kb][j]); } while (0)
; DEV void diff16_pass(const bf16_t* __restrict__ proj, int qcol, int kcol, int vcol, int q0, f32x4 (&o)[2][8], f32x4 (&l_out)[2], unsigned char* lds) {
;     ...
;   float m_reg[2] = {0.f, 0.f};
;   f32x4 ol[2] = {(f32x4){0.f, 0.f, 0.f, 0.f}, (f32x4){0.f, 0.f, 0.f, 0.f}};
;   const bf16x8 ones = {0x3F80, 0x3F80, 0x3F80, 0x3F80, 0x3F80, 0x3F80, 0x3F80, 0x3F80};
;   f32x4 negm[2] = {(f32x4){0.f, 0.f, 0.f, 0.f}, (f32x4){0.f, 0.f, 0.f, 0.f}};
; #pragma unroll
;   for (int g = 0; g < 2; ++g)
; #pragma unroll
;     for (int cb = 0; cb < 8; ++cb) o[g][cb] = (f32x4){0.f, 0.f, 0.f, 0.f};
;   f32x4 SA[2][4], SB2[2][4]; float alA[2], alB[2]; bool rfA = false, rfB = false; bf16x8 pa[2][2];
;   DMA(0); DMA(1); DMA(2); VWAIT(3); LBAR();
;   { QKT16(SA, 0); float pm_[2]; ROWMAXF16(SA, pm_); RESCALE16(SA, pm_, alA, rfA, true); alA[0] = 1.f; alA[1] = 1.f; rfA = false; EXP16(SA); }
	ds_read_b128 v[24:27], v228
	ds_read_b128 v[28:31], v228 offset:1024
	ds_read_b128 v[32:35], v228 offset:2048
	ds_read_b128 v[36:39], v228 offset:3072
	ds_read_b128 v[0:3], v50
	ds_read_b128 v[4:7], v51
	s_waitcnt lgkmcnt(0)
	v_mfma_f32_16x16x32_bf16 v[8:11], v[0:3], v[24:27], 0
	v_mfma_f32_16x16x32_bf16 v[12:15], v[0:3], v[32:35], 0
	v_mfma_f32_16x16x32_bf16 v[0:3], v[4:7], v[28:31], v[8:11]
	v_mfma_f32_16x16x32_bf16 v[4:7], v[4:7], v[36:39], v[12:15]
	s_nop 4
	ds_read_b128 v[8:11], v50 offset:512
	ds_read_b128 v[12:15], v51 offset:512
	s_waitcnt lgkmcnt(0)
	v_mfma_f32_16x16x32_bf16 v[16:19], v[8:11], v[24:27], 0
	v_mfma_f32_16x16x32_bf16 v[20:23], v[8:11], v[32:35], 0
	v_mfma_f32_16x16x32_bf16 v[8:11], v[12:15], v[28:31], v[16:19]
	v_mfma_f32_16x16x32_bf16 v[16:19], v[12:15], v[36:39], v[20:23]
	ds_read_b128 v[12:15], v50 offset:4096
	s_nop 4
	ds_read_b128 v[20:23], v51 offset:4096
	s_waitcnt lgkmcnt(0)
	v_mfma_f32_16x16x32_bf16 v[40:43], v[12:15], v[24:27], 0
	v_mfma_f32_16x16x32_bf16 v[44:47], v[12:15], v[32:35], 0
	v_mfma_f32_16x16x32_bf16 v[12:15], v[20:23], v[28:31], v[40:43]
	v_mfma_f32_16x16x32_bf16 v[20:23], v[20:23], v[36:39], v[44:47]
	s_nop 4
	ds_read_b128 v[40:43], v50 offset:4608
	ds_read_b128 v[44:47], v51 offset:4608
	s_waitcnt lgkmcnt(0)
	v_mfma_f32_16x16x32_bf16 v[24:27], v[40:43], v[24:27], 0
	v_mfma_f32_16x16x32_bf16 v[32:35], v[40:43], v[32:35], 0
	v_mfma_f32_16x16x32_bf16 v[24:27], v[44:47], v[28:31], v[24:27]
	v_mfma_f32_16x16x32_bf16 v[28:31], v[44:47], v[36:39], v[32:35]
	s_nop 5
	v_max_f32_e32 v32, v1, v1
	v_max_f32_e32 v33, v0, v0
	v_max_f32_e32 v32, v33, v32
	v_max_f32_e32 v33, v5, v5
	v_max_f32_e32 v34, v4, v4
	v_max_f32_e32 v33, v34, v33
	v_max3_f32 v32, v32, v2, v3
	v_max3_f32 v33, v33, v6, v7
	v_max3_f32 v32, v32, v8, v9
	v_max3_f32 v33, v33, v16, v17
	v_max3_f32 v32, v32, v10, v11
	v_max3_f32 v33, v33, v18, v19
	v_max3_f32 v32, v32, v12, v13
	v_max3_f32 v33, v33, v20, v21
	v_max3_f32 v32, v32, v14, v15
	v_max3_f32 v33, v33, v22, v23
	v_max3_f32 v32, v32, v24, v25
	v_max3_f32 v33, v33, v28, v29
	v_max3_f32 v32, v32, v26, v27
	v_max3_f32 v34, v33, v30, v31
	ds_bpermute_b32 v33, v217, v32
	ds_bpermute_b32 v35, v217, v34
	s_waitcnt lgkmcnt(0)
	v_max_f32_e32 v33, v33, v33
	v_max_f32_e32 v35, v35, v35
	v_max_f32_e32 v32, v32, v33
	v_max_f32_e32 v34, v34, v35
	ds_bpermute_b32 v33, v216, v32
	ds_bpermute_b32 v35, v216, v34
	s_cbranch_vccnz .LBB0_418
	s_waitcnt lgkmcnt(0)
	v_max_f32_e32 v35, v35, v35
	v_max_f32_e32 v34, v34, v34
	v_max_f32_e32 v35, v34, v35
	v_sub_f32_e32 v5, v5, v35
	v_sub_f32_e32 v4, v4, v35
	v_exp_f32_e32 v137, v4
	v_exp_f32_e32 v148, v5
	v_max_f32_e32 v4, v33, v33
	v_max_f32_e32 v5, v32, v32
	v_sub_f32_e32 v7, v7, v35
	v_sub_f32_e32 v6, v6, v35
	v_max_f32_e32 v34, v5, v4
	v_exp_f32_e32 v149, v6
	v_exp_f32_e32 v151, v7
	v_sub_f32_e32 v4, v27, v34
	v_sub_f32_e32 v5, v26, v34
	v_sub_f32_e32 v6, v25, v34
	v_sub_f32_e32 v7, v24, v34
	v_exp_f32_e32 v152, v7
	v_exp_f32_e32 v154, v6
	v_exp_f32_e32 v155, v5
	v_exp_f32_e32 v157, v4
	v_sub_f32_e32 v4, v15, v34
	v_sub_f32_e32 v5, v14, v34
	v_sub_f32_e32 v6, v13, v34
	v_sub_f32_e32 v7, v12, v34
	v_sub_f32_e32 v31, v31, v35
	v_sub_f32_e32 v30, v30, v35
	v_sub_f32_e32 v29, v29, v35
	v_sub_f32_e32 v28, v28, v35
	v_sub_f32_e32 v23, v23, v35
	v_sub_f32_e32 v22, v22, v35
	v_sub_f32_e32 v21, v21, v35
	v_sub_f32_e32 v20, v20, v35
	v_sub_f32_e32 v19, v19, v35
	v_sub_f32_e32 v18, v18, v35
	v_sub_f32_e32 v17, v17, v35
	v_sub_f32_e32 v16, v16, v35
	v_exp_f32_e32 v153, v7
	v_exp_f32_e32 v156, v6
	v_exp_f32_e32 v158, v5
	v_exp_f32_e32 v159, v4
	v_sub_f32_e32 v4, v11, v34
	v_sub_f32_e32 v5, v10, v34
	v_sub_f32_e32 v6, v9, v34
	v_sub_f32_e32 v7, v8, v34
	v_sub_f32_e32 v3, v3, v34
	v_sub_f32_e32 v2, v2, v34
	v_sub_f32_e32 v1, v1, v34
	v_sub_f32_e32 v0, v0, v34
	v_exp_f32_e32 v128, v28
	v_exp_f32_e32 v130, v29
	v_exp_f32_e32 v131, v30
	v_exp_f32_e32 v133, v31
	v_exp_f32_e32 v129, v20
	v_exp_f32_e32 v134, v21
	v_exp_f32_e32 v135, v22
	v_exp_f32_e32 v138, v23
	v_exp_f32_e32 v132, v16
	v_exp_f32_e32 v136, v17
	v_exp_f32_e32 v139, v18
	v_exp_f32_e32 v150, v19
	v_exp_f32_e32 v240, v7
	v_exp_f32_e32 v242, v6
	v_exp_f32_e32 v243, v5
	v_exp_f32_e32 v246, v4
	v_exp_f32_e32 v241, v0
	v_exp_f32_e32 v244, v1
	v_exp_f32_e32 v245, v2
	v_exp_f32_e32 v247, v3
	v_lshrrev_b32_e32 v36, 3, v226
	v_pk_add_f32 v[208:209], v[34:35], 0 op_sel_hi:[1,0]
	v_mov_b32_e32 v2, v193
	v_mov_b32_e32 v3, v193
	v_or_b32_e32 v235, s75, v36
	v_xor_b32_e32 v76, 0x80000000, v209
	v_pk_add_f32 v[72:73], v[208:209], 0 neg_lo:[1,1] neg_hi:[1,1]
	v_mov_b32_e32 v0, v193
	v_mov_b32_e32 v1, v193
	v_mov_b64_e32 v[10:11], v[2:3]
	v_mov_b64_e32 v[26:27], v[2:3]
	v_mov_b64_e32 v[18:19], v[2:3]
	v_mov_b64_e32 v[38:39], v[2:3]
	v_mov_b64_e32 v[42:43], v[2:3]
	v_mov_b64_e32 v[50:51], v[2:3]
	v_mov_b64_e32 v[66:67], v[2:3]
	v_mov_b64_e32 v[6:7], v[2:3]
	v_mov_b64_e32 v[14:15], v[2:3]
	v_mov_b64_e32 v[30:31], v[2:3]
	v_mov_b64_e32 v[22:23], v[2:3]
	v_mov_b64_e32 v[34:35], v[2:3]
	v_mov_b64_e32 v[46:47], v[2:3]
	v_mov_b64_e32 v[54:55], v[2:3]
	v_mov_b64_e32 v[62:63], v[2:3]
	v_mov_b64_e32 v[70:71], v[2:3]
	v_mov_b64_e32 v[58:59], v[2:3]
	v_or_b32_e32 v236, 2, v235
	v_cmp_gt_u32_e64 s[4:5], 16, v227
	v_lshl_add_u32 v237, v226, 2, v225
	s_mov_b32 s19, 1
	s_mov_b64 s[6:7], 0
	v_mov_b32_e32 v249, 1.0
	s_mov_b32 s15, 0x10000
	s_movk_i32 s16, 0x4000
	v_mov_b64_e32 v[8:9], v[0:1]
	v_mov_b64_e32 v[24:25], v[0:1]
	v_mov_b64_e32 v[16:17], v[0:1]
	v_mov_b64_e32 v[36:37], v[0:1]
	v_mov_b64_e32 v[40:41], v[0:1]
	v_mov_b64_e32 v[48:49], v[0:1]
	v_mov_b64_e32 v[64:65], v[0:1]
	v_mov_b64_e32 v[4:5], v[0:1]
	v_mov_b64_e32 v[12:13], v[0:1]
	v_mov_b64_e32 v[28:29], v[0:1]
	v_mov_b64_e32 v[20:21], v[0:1]
	v_mov_b64_e32 v[32:33], v[0:1]
	v_mov_b64_e32 v[44:45], v[0:1]
	v_mov_b64_e32 v[52:53], v[0:1]
	v_mov_b64_e32 v[60:61], v[0:1]
	v_mov_b32_e32 v248, 1.0
	v_mov_b64_e32 v[68:69], v[0:1]
	v_mov_b64_e32 v[56:57], v[0:1]
	v_mov_b32_e32 v73, v72
	v_mov_b32_e32 v74, v72
	v_mov_b32_e32 v75, v72
	v_mov_b32_e32 v77, v76
	v_mov_b32_e32 v78, v76
	v_mov_b32_e32 v79, v76
	s_cmp_lt_u32 s13, 0x1000
	s_cbranch_scc0 .Lprio_b
	s_setprio 1
